# accumulator zeroing interleaved into the store-bound swiglu (P1,P9) and lean P3 epilogues right after each accumulator's last read; the 128-v_mov zero block after the last store is skipped
# speedup vs baseline: 1.0118x; 1.0118x over previous
; __device__ __forceinline__ unsigned pk2(float lo, float hi) { f32x2_t v = {lo, hi}; bf16x2_t b = __builtin_convertvector(v, bf16x2_t); return __builtin_bit_cast(unsigned, b); }
; __device__ __forceinline__ float siluf_(float x) { return x * sigmoidf_(x); }
;     __device__ __forceinline__ void operator()(Acc& acc, const Unit& u, int wr, int wc, int fr, int fq, const float (&rsa)[2][4]) const {
;         const int row0 = u.pm * BM + wr * 64 + fr, col0 = u.pn * HALF + wc * 32 + 8 * fq;
; #pragma unroll
;         for (int ai = 0; ai < 2; ++ai)
; #pragma unroll
;             for (int m = 0; m < 4; ++m) {
;                 const int row = row0 + ai * HALF + m * 16; const float rs = rsa[ai][m];
;                 float o[8];
; #pragma unroll
;                 for (int n = 0; n < 2; ++n)
; #pragma unroll
;                     for (int j = 0; j < 4; ++j) { const float g = acc[ai][0][m][n][j] * rs, up = acc[ai][1][m][n][j] * rs; o[n * 4 + j] = siluf_(g) * up; }
;                 u32x4 w; w.x = pk2(o[0], o[1]); w.y = pk2(o[2], o[3]); w.z = pk2(o[4], o[5]); w.w = pk2(o[6], o[7]);
;                 const int rr = row & (BM - 1);
;                 *(u32x4*)((char*)O + ((size_t)(u.pm * (FF / BK) + (col0 >> 6))) * (2 * HTB) + (rr >> 7) * HTB + lds_byte(rr & 127, col0 & 63)) = w;
;             }
; template <class Epi, bool ALIGN_EPI, bool ABLK = false>
; __device__ __forceinline__ void gemm_phase(PG8_LAS unsigned char* lds, const Gemm g, const StaticOrder& S, const Epi& E) {
;     ...
;         if (!E.keep(cur)) {
; #pragma unroll
;             for (int a = 0; a < 2; ++a)
; #pragma unroll
;                 for (int b = 0; b < 2; ++b)
; #pragma unroll
;                     for (int m = 0; m < 4; ++m)
; #pragma unroll
;                         for (int n = 0; n < 2; ++n) acc[a][b][m][n] = (f32x4){0.f, 0.f, 0.f, 0.f};
;         }
.LBB0_409:
	v_pk_mul_f32 v[140:141], v[126:127], v[134:135] op_sel_hi:[1,0]
	v_mov_b64_e32 v[126:127], 0
	v_pk_mul_f32 v[144:145], v[94:95], v[134:135] op_sel_hi:[1,0]
	v_mov_b64_e32 v[94:95], 0
	v_mul_f32_e32 v131, 0xbfb8aa3b, v140
	v_exp_f32_e32 v131, v131
	v_pk_mul_f32 v[186:187], v[96:97], v[134:135] op_sel_hi:[1,0]
	v_mov_b64_e32 v[96:97], 0
	v_pk_mul_f32 v[188:189], v[90:91], v[134:135] op_sel_hi:[1,0]
	v_mov_b64_e32 v[90:91], 0
	s_lshl_b32 s39, s10, 7
	v_add_f32_e32 v131, 1.0, v131
	v_rcp_f32_e32 v142, v131
	v_mul_f32_e32 v131, 0xbfb8aa3b, v141
	v_exp_f32_e32 v131, v131
	s_or_b32 s39, s39, s17
	s_ashr_i32 s39, s39, 6
	s_mul_i32 s41, s8, 44
	v_add_f32_e32 v131, 1.0, v131
	v_rcp_f32_e32 v143, v131
	s_add_i32 s46, s39, s41
	s_ashr_i32 s47, s46, 31
	s_lshl_b64 s[46:47], s[46:47], 15
	v_pk_mul_f32 v[140:141], v[140:141], v[142:143]
	v_pk_mul_f32 v[142:143], v[128:129], v[134:135] op_sel_hi:[1,0]
	v_mov_b64_e32 v[128:129], 0
	v_pk_mul_f32 v[140:141], v[144:145], v[140:141]
	v_mul_f32_e32 v131, 0xbfb8aa3b, v142
	v_exp_f32_e32 v131, v131
	s_add_u32 s39, s14, s46
	s_addc_u32 s41, s15, s47
	s_add_u32 s46, s39, s62
	v_add_f32_e32 v131, 1.0, v131
	v_rcp_f32_e32 v144, v131
	v_mul_f32_e32 v131, 0xbfb8aa3b, v143
	v_exp_f32_e32 v131, v131
	s_addc_u32 s47, s41, 0
	v_cvt_pk_bf16_f32 v140, v140, v141
	v_add_f32_e32 v131, 1.0, v131
	v_rcp_f32_e32 v145, v131
	s_nop 0
	v_pk_mul_f32 v[142:143], v[142:143], v[144:145]
	v_pk_mul_f32 v[144:145], v[122:123], v[134:135] op_sel_hi:[1,0]
	v_mov_b64_e32 v[122:123], 0
	v_pk_mul_f32 v[142:143], v[186:187], v[142:143]
	v_mul_f32_e32 v131, 0xbfb8aa3b, v144
	v_exp_f32_e32 v131, v131
	v_cvt_pk_bf16_f32 v141, v142, v143
	v_add_f32_e32 v131, 1.0, v131
	v_rcp_f32_e32 v186, v131
	v_mul_f32_e32 v131, 0xbfb8aa3b, v145
	v_exp_f32_e32 v131, v131
	s_nop 0
	v_add_f32_e32 v131, 1.0, v131
	v_rcp_f32_e32 v187, v131
	s_nop 0
	v_pk_mul_f32 v[144:145], v[144:145], v[186:187]
	v_pk_mul_f32 v[186:187], v[124:125], v[134:135] op_sel_hi:[1,0]
	v_mov_b64_e32 v[124:125], 0
	v_pk_mul_f32 v[144:145], v[188:189], v[144:145]
	v_mul_f32_e32 v131, 0xbfb8aa3b, v186
	v_exp_f32_e32 v131, v131
	v_pk_mul_f32 v[134:135], v[92:93], v[134:135] op_sel_hi:[1,0]
	v_mov_b64_e32 v[92:93], 0
	v_cvt_pk_bf16_f32 v142, v144, v145
	v_pk_mul_f32 v[144:145], v[88:89], v[170:171] op_sel_hi:[1,0]
	v_mov_b64_e32 v[88:89], 0
	v_add_f32_e32 v131, 1.0, v131
	v_rcp_f32_e32 v188, v131
	v_mul_f32_e32 v131, 0xbfb8aa3b, v187
	v_exp_f32_e32 v131, v131
	s_nop 0
	v_add_f32_e32 v131, 1.0, v131
	v_rcp_f32_e32 v189, v131
	s_nop 0
	v_pk_mul_f32 v[186:187], v[186:187], v[188:189]
	s_nop 0
	v_pk_mul_f32 v[134:135], v[134:135], v[186:187]
	v_pk_mul_f32 v[186:187], v[82:83], v[170:171] op_sel_hi:[1,0]
	v_mov_b64_e32 v[82:83], 0
	v_cvt_pk_bf16_f32 v143, v134, v135
	v_lshl_add_u64 v[134:135], s[46:47], 0, v[152:153]
	global_store_dwordx4 v[134:135], v[140:143], off
	v_pk_mul_f32 v[134:135], v[118:119], v[170:171] op_sel_hi:[1,0]
	v_mov_b64_e32 v[118:119], 0
	v_pk_mul_f32 v[188:189], v[84:85], v[170:171] op_sel_hi:[1,0]
	v_mov_b64_e32 v[84:85], 0
	v_mul_f32_e32 v131, 0xbfb8aa3b, v134
	v_exp_f32_e32 v131, v131
	v_pk_mul_f32 v[142:143], v[86:87], v[170:171] op_sel_hi:[1,0]
	v_mov_b64_e32 v[86:87], 0
	v_add_f32_e32 v131, 1.0, v131
	v_rcp_f32_e32 v140, v131
	v_mul_f32_e32 v131, 0xbfb8aa3b, v135
	v_exp_f32_e32 v131, v131
	s_nop 0
	v_add_f32_e32 v131, 1.0, v131
	v_rcp_f32_e32 v141, v131
	s_nop 0
	v_pk_mul_f32 v[134:135], v[134:135], v[140:141]
	v_pk_mul_f32 v[140:141], v[120:121], v[170:171] op_sel_hi:[1,0]
	v_mov_b64_e32 v[120:121], 0
	v_pk_mul_f32 v[134:135], v[142:143], v[134:135]
	v_mul_f32_e32 v131, 0xbfb8aa3b, v140
	v_exp_f32_e32 v131, v131
	s_nop 0
	v_add_f32_e32 v131, 1.0, v131
	v_rcp_f32_e32 v142, v131
	v_mul_f32_e32 v131, 0xbfb8aa3b, v141
	v_exp_f32_e32 v131, v131
	s_nop 0
	v_add_f32_e32 v131, 1.0, v131
	v_rcp_f32_e32 v143, v131
	s_nop 0
	v_pk_mul_f32 v[140:141], v[140:141], v[142:143]
	s_nop 0
	v_pk_mul_f32 v[142:143], v[144:145], v[140:141]
	v_pk_mul_f32 v[140:141], v[114:115], v[170:171] op_sel_hi:[1,0]
	v_mov_b64_e32 v[114:115], 0
	s_nop 0
	v_mul_f32_e32 v131, 0xbfb8aa3b, v140
	v_exp_f32_e32 v131, v131
	s_nop 0
	v_add_f32_e32 v131, 1.0, v131
	v_rcp_f32_e32 v144, v131
	v_mul_f32_e32 v131, 0xbfb8aa3b, v141
	v_exp_f32_e32 v131, v131
	s_nop 0
	v_add_f32_e32 v131, 1.0, v131
	v_rcp_f32_e32 v145, v131
	s_nop 0
	v_pk_mul_f32 v[140:141], v[140:141], v[144:145]
	s_nop 0
	v_pk_mul_f32 v[144:145], v[186:187], v[140:141]
	v_pk_mul_f32 v[140:141], v[116:117], v[170:171] op_sel_hi:[1,0]
	v_mov_b64_e32 v[116:117], 0
	s_nop 0
	v_mul_f32_e32 v131, 0xbfb8aa3b, v140
	v_exp_f32_e32 v131, v131
	s_nop 0
	v_add_f32_e32 v131, 1.0, v131
	v_rcp_f32_e32 v186, v131
	v_mul_f32_e32 v131, 0xbfb8aa3b, v141
	v_exp_f32_e32 v131, v131
	s_nop 0
	v_add_f32_e32 v131, 1.0, v131
	v_rcp_f32_e32 v187, v131
	s_nop 0
	v_pk_mul_f32 v[140:141], v[140:141], v[186:187]
	s_nop 0
	v_pk_mul_f32 v[186:187], v[188:189], v[140:141]
	v_cvt_pk_bf16_f32 v140, v134, v135
	v_cvt_pk_bf16_f32 v141, v142, v143
	v_cvt_pk_bf16_f32 v142, v144, v145
	v_cvt_pk_bf16_f32 v143, v186, v187
	v_lshl_add_u64 v[134:135], s[46:47], 0, v[156:157]
	global_store_dwordx4 v[134:135], v[140:143], off
	v_pk_mul_f32 v[134:135], v[110:111], v[136:137] op_sel_hi:[1,0]
	v_mov_b64_e32 v[110:111], 0
	v_pk_mul_f32 v[144:145], v[80:81], v[136:137] op_sel_hi:[1,0]
	v_mov_b64_e32 v[80:81], 0
	v_mul_f32_e32 v131, 0xbfb8aa3b, v134
	v_exp_f32_e32 v131, v131
	v_pk_mul_f32 v[142:143], v[78:79], v[136:137] op_sel_hi:[1,0]
	v_mov_b64_e32 v[78:79], 0
	v_pk_mul_f32 v[186:187], v[74:75], v[136:137] op_sel_hi:[1,0]
	v_mov_b64_e32 v[74:75], 0
	v_add_f32_e32 v131, 1.0, v131
; __device__ __forceinline__ unsigned pk2(float lo, float hi) { f32x2_t v = {lo, hi}; bf16x2_t b = __builtin_convertvector(v, bf16x2_t); return __builtin_bit_cast(unsigned, b); }
; __device__ __forceinline__ float siluf_(float x) { return x * sigmoidf_(x); }
;     __device__ __forceinline__ void operator()(Acc& acc, const Unit& u, int wr, int wc, int fr, int fq, const float (&rsa)[2][4]) const {
;     ...
;             for (int m = 0; m < 4; ++m) {
;                 const int row = row0 + ai * HALF + m * 16; const float rs = rsa[ai][m];
;                 float o[8];
; #pragma unroll
;                 for (int n = 0; n < 2; ++n)
; #pragma unroll
;                     for (int j = 0; j < 4; ++j) { const float g = acc[ai][0][m][n][j] * rs, up = acc[ai][1][m][n][j] * rs; o[n * 4 + j] = siluf_(g) * up; }
;                 u32x4 w; w.x = pk2(o[0], o[1]); w.y = pk2(o[2], o[3]); w.z = pk2(o[4], o[5]); w.w = pk2(o[6], o[7]);
;                 const int rr = row & (BM - 1);
;                 *(u32x4*)((char*)O + ((size_t)(u.pm * (FF / BK) + (col0 >> 6))) * (2 * HTB) + (rr >> 7) * HTB + lds_byte(rr & 127, col0 & 63)) = w;
;             }
	v_rcp_f32_e32 v140, v131
	v_mul_f32_e32 v131, 0xbfb8aa3b, v135
	v_exp_f32_e32 v131, v131
	s_nop 0
	v_add_f32_e32 v131, 1.0, v131
	v_rcp_f32_e32 v141, v131
	s_nop 0
	v_pk_mul_f32 v[134:135], v[134:135], v[140:141]
	v_pk_mul_f32 v[140:141], v[112:113], v[136:137] op_sel_hi:[1,0]
	v_mov_b64_e32 v[112:113], 0
	v_pk_mul_f32 v[134:135], v[142:143], v[134:135]
	v_mul_f32_e32 v131, 0xbfb8aa3b, v140
	v_exp_f32_e32 v131, v131
	v_cvt_pk_bf16_f32 v134, v134, v135
	v_add_f32_e32 v131, 1.0, v131
	v_rcp_f32_e32 v142, v131
	v_mul_f32_e32 v131, 0xbfb8aa3b, v141
	v_exp_f32_e32 v131, v131
	s_nop 0
	v_add_f32_e32 v131, 1.0, v131
	v_rcp_f32_e32 v143, v131
	s_nop 0
	v_pk_mul_f32 v[140:141], v[140:141], v[142:143]
	v_pk_mul_f32 v[142:143], v[106:107], v[136:137] op_sel_hi:[1,0]
	v_mov_b64_e32 v[106:107], 0
	v_pk_mul_f32 v[140:141], v[144:145], v[140:141]
	v_mul_f32_e32 v131, 0xbfb8aa3b, v142
	v_exp_f32_e32 v131, v131
	v_cvt_pk_bf16_f32 v135, v140, v141
	v_lshl_add_u64 v[140:141], s[46:47], 0, v[158:159]
	v_add_f32_e32 v131, 1.0, v131
	v_rcp_f32_e32 v144, v131
	v_mul_f32_e32 v131, 0xbfb8aa3b, v143
	v_exp_f32_e32 v131, v131
	s_nop 0
	v_add_f32_e32 v131, 1.0, v131
	v_rcp_f32_e32 v145, v131
	s_nop 0
	v_pk_mul_f32 v[142:143], v[142:143], v[144:145]
	v_pk_mul_f32 v[144:145], v[108:109], v[136:137] op_sel_hi:[1,0]
	v_mov_b64_e32 v[108:109], 0
	v_pk_mul_f32 v[142:143], v[186:187], v[142:143]
	v_mul_f32_e32 v131, 0xbfb8aa3b, v144
	v_exp_f32_e32 v131, v131
	v_pk_mul_f32 v[136:137], v[76:77], v[136:137] op_sel_hi:[1,0]
	v_mov_b64_e32 v[76:77], 0
	v_add_f32_e32 v131, 1.0, v131
	v_rcp_f32_e32 v186, v131
	v_mul_f32_e32 v131, 0xbfb8aa3b, v145
	v_exp_f32_e32 v131, v131
	s_nop 0
	v_add_f32_e32 v131, 1.0, v131
	v_rcp_f32_e32 v187, v131
	s_nop 0
	v_pk_mul_f32 v[144:145], v[144:145], v[186:187]
	s_nop 0
	v_pk_mul_f32 v[144:145], v[136:137], v[144:145]
	v_cvt_pk_bf16_f32 v136, v142, v143
	v_cvt_pk_bf16_f32 v137, v144, v145
	global_store_dwordx4 v[140:141], v[134:137], off
	v_pk_mul_f32 v[140:141], v[70:71], v[168:169] op_sel_hi:[1,0]
	v_mov_b64_e32 v[70:71], 0
	v_pk_mul_f32 v[142:143], v[72:73], v[168:169] op_sel_hi:[1,0]
	v_mov_b64_e32 v[72:73], 0
	v_pk_mul_f32 v[134:135], v[102:103], v[168:169] op_sel_hi:[1,0]
	v_mov_b64_e32 v[102:103], 0
	v_pk_mul_f32 v[144:145], v[66:67], v[168:169] op_sel_hi:[1,0]
	v_mov_b64_e32 v[66:67], 0
	v_mul_f32_e32 v131, 0xbfb8aa3b, v134
	v_exp_f32_e32 v131, v131
	v_pk_mul_f32 v[186:187], v[68:69], v[168:169] op_sel_hi:[1,0]
	v_mov_b64_e32 v[68:69], 0
	v_add_f32_e32 v131, 1.0, v131
	v_rcp_f32_e32 v136, v131
	v_mul_f32_e32 v131, 0xbfb8aa3b, v135
	v_exp_f32_e32 v131, v131
	s_nop 0
	v_add_f32_e32 v131, 1.0, v131
	v_rcp_f32_e32 v137, v131
	s_nop 0
	v_pk_mul_f32 v[134:135], v[134:135], v[136:137]
	v_pk_mul_f32 v[136:137], v[104:105], v[168:169] op_sel_hi:[1,0]
	v_mov_b64_e32 v[104:105], 0
	v_pk_mul_f32 v[134:135], v[140:141], v[134:135]
	v_mul_f32_e32 v131, 0xbfb8aa3b, v136
	v_exp_f32_e32 v131, v131
	v_cvt_pk_bf16_f32 v134, v134, v135
	v_add_f32_e32 v131, 1.0, v131
	v_rcp_f32_e32 v140, v131
	v_mul_f32_e32 v131, 0xbfb8aa3b, v137
	v_exp_f32_e32 v131, v131
	s_nop 0
	v_add_f32_e32 v131, 1.0, v131
	v_rcp_f32_e32 v141, v131
	s_nop 0
	v_pk_mul_f32 v[136:137], v[136:137], v[140:141]
	v_pk_mul_f32 v[140:141], v[98:99], v[168:169] op_sel_hi:[1,0]
	v_mov_b64_e32 v[98:99], 0
	v_pk_mul_f32 v[136:137], v[142:143], v[136:137]
	v_mul_f32_e32 v131, 0xbfb8aa3b, v140
	v_exp_f32_e32 v131, v131
	v_cvt_pk_bf16_f32 v135, v136, v137
	v_add_f32_e32 v131, 1.0, v131
	v_rcp_f32_e32 v142, v131
	v_mul_f32_e32 v131, 0xbfb8aa3b, v141
	v_exp_f32_e32 v131, v131
	s_nop 0
	v_add_f32_e32 v131, 1.0, v131
	v_rcp_f32_e32 v143, v131
	s_nop 0
	v_pk_mul_f32 v[140:141], v[140:141], v[142:143]
	v_pk_mul_f32 v[142:143], v[100:101], v[168:169] op_sel_hi:[1,0]
	v_mov_b64_e32 v[100:101], 0
	v_pk_mul_f32 v[140:141], v[144:145], v[140:141]
	v_mul_f32_e32 v131, 0xbfb8aa3b, v142
	v_exp_f32_e32 v131, v131
	v_cvt_pk_bf16_f32 v136, v140, v141
	v_lshl_add_u64 v[140:141], s[46:47], 0, v[160:161]
	s_add_u32 s46, s39, s63
	v_add_f32_e32 v131, 1.0, v131
	v_rcp_f32_e32 v144, v131
	v_mul_f32_e32 v131, 0xbfb8aa3b, v143
	v_exp_f32_e32 v131, v131
	s_addc_u32 s47, s41, 0
	s_andn2_b64 vcc, exec, s[6:7]
	v_add_f32_e32 v131, 1.0, v131
	v_rcp_f32_e32 v145, v131
	s_nop 0
	v_pk_mul_f32 v[142:143], v[142:143], v[144:145]
	s_nop 0
	v_pk_mul_f32 v[142:143], v[186:187], v[142:143]
	s_nop 0
	v_cvt_pk_bf16_f32 v137, v142, v143
	global_store_dwordx4 v[140:141], v[134:137], off
	s_nop 1
	v_pk_mul_f32 v[134:135], v[62:63], v[130:131] op_sel_hi:[1,0]
	v_mov_b64_e32 v[62:63], 0
	s_nop 0
	v_mul_f32_e32 v131, 0xbfb8aa3b, v134
	v_exp_f32_e32 v131, v131
	s_nop 0
	v_add_f32_e32 v131, 1.0, v131
	v_rcp_f32_e32 v136, v131
	v_pk_mul_f32 v[140:141], v[30:31], v[130:131] op_sel_hi:[1,0]
	v_mov_b64_e32 v[30:31], 0
	v_mul_f32_e32 v131, 0xbfb8aa3b, v135
	v_exp_f32_e32 v131, v131
	s_nop 0
	v_add_f32_e32 v131, 1.0, v131
	v_rcp_f32_e32 v137, v131
	s_nop 0
	v_pk_mul_f32 v[134:135], v[134:135], v[136:137]
	v_pk_mul_f32 v[136:137], v[64:65], v[130:131] op_sel_hi:[1,0]
	v_mov_b64_e32 v[64:65], 0
	v_pk_mul_f32 v[134:135], v[140:141], v[134:135]
	v_mul_f32_e32 v131, 0xbfb8aa3b, v136
	v_exp_f32_e32 v131, v131
	v_cvt_pk_bf16_f32 v134, v134, v135
	v_add_f32_e32 v131, 1.0, v131
	v_rcp_f32_e32 v140, v131
	v_pk_mul_f32 v[142:143], v[32:33], v[130:131] op_sel_hi:[1,0]
	v_mov_b64_e32 v[32:33], 0
	v_mul_f32_e32 v131, 0xbfb8aa3b, v137
	v_exp_f32_e32 v131, v131
	s_nop 0
	v_add_f32_e32 v131, 1.0, v131
	v_rcp_f32_e32 v141, v131
	s_nop 0
	v_pk_mul_f32 v[136:137], v[136:137], v[140:141]
	v_pk_mul_f32 v[140:141], v[58:59], v[130:131] op_sel_hi:[1,0]
	v_mov_b64_e32 v[58:59], 0
; __device__ __forceinline__ unsigned pk2(float lo, float hi) { f32x2_t v = {lo, hi}; bf16x2_t b = __builtin_convertvector(v, bf16x2_t); return __builtin_bit_cast(unsigned, b); }
; __device__ __forceinline__ float siluf_(float x) { return x * sigmoidf_(x); }
;     __device__ __forceinline__ void operator()(Acc& acc, const Unit& u, int wr, int wc, int fr, int fq, const float (&rsa)[2][4]) const {
;     ...
;             for (int m = 0; m < 4; ++m) {
;                 const int row = row0 + ai * HALF + m * 16; const float rs = rsa[ai][m];
;                 float o[8];
; #pragma unroll
;                 for (int n = 0; n < 2; ++n)
; #pragma unroll
;                     for (int j = 0; j < 4; ++j) { const float g = acc[ai][0][m][n][j] * rs, up = acc[ai][1][m][n][j] * rs; o[n * 4 + j] = siluf_(g) * up; }
;                 u32x4 w; w.x = pk2(o[0], o[1]); w.y = pk2(o[2], o[3]); w.z = pk2(o[4], o[5]); w.w = pk2(o[6], o[7]);
;                 const int rr = row & (BM - 1);
;                 *(u32x4*)((char*)O + ((size_t)(u.pm * (FF / BK) + (col0 >> 6))) * (2 * HTB) + (rr >> 7) * HTB + lds_byte(rr & 127, col0 & 63)) = w;
;             }
	v_pk_mul_f32 v[136:137], v[142:143], v[136:137]
	v_mul_f32_e32 v131, 0xbfb8aa3b, v140
	v_exp_f32_e32 v131, v131
	v_cvt_pk_bf16_f32 v135, v136, v137
	v_add_f32_e32 v131, 1.0, v131
	v_rcp_f32_e32 v142, v131
	v_pk_mul_f32 v[144:145], v[26:27], v[130:131] op_sel_hi:[1,0]
	v_mov_b64_e32 v[26:27], 0
	v_mul_f32_e32 v131, 0xbfb8aa3b, v141
	v_exp_f32_e32 v131, v131
	s_nop 0
	v_add_f32_e32 v131, 1.0, v131
	v_rcp_f32_e32 v143, v131
	s_nop 0
	v_pk_mul_f32 v[140:141], v[140:141], v[142:143]
	v_pk_mul_f32 v[142:143], v[60:61], v[130:131] op_sel_hi:[1,0]
	v_mov_b64_e32 v[60:61], 0
	v_pk_mul_f32 v[140:141], v[144:145], v[140:141]
	v_mul_f32_e32 v131, 0xbfb8aa3b, v142
	v_mul_f32_e32 v133, 0xbfb8aa3b, v143
	v_exp_f32_e32 v131, v131
	v_exp_f32_e32 v133, v133
	v_cvt_pk_bf16_f32 v136, v140, v141
	v_pk_mul_f32 v[140:141], v[24:25], v[166:167] op_sel_hi:[1,0]
	v_mov_b64_e32 v[24:25], 0
	v_add_f32_e32 v131, 1.0, v131
	v_add_f32_e32 v133, 1.0, v133
	v_rcp_f32_e32 v144, v131
	v_rcp_f32_e32 v145, v133
	v_pk_mul_f32 v[130:131], v[28:29], v[130:131] op_sel_hi:[1,0]
	v_mov_b64_e32 v[28:29], 0
	v_pk_mul_f32 v[142:143], v[142:143], v[144:145]
	s_nop 0
	v_pk_mul_f32 v[130:131], v[130:131], v[142:143]
	v_pk_mul_f32 v[142:143], v[18:19], v[166:167] op_sel_hi:[1,0]
	v_mov_b64_e32 v[18:19], 0
	v_cvt_pk_bf16_f32 v137, v130, v131
	v_lshl_add_u64 v[130:131], s[46:47], 0, v[152:153]
	global_store_dwordx4 v[130:131], v[134:137], off
	v_pk_mul_f32 v[130:131], v[54:55], v[166:167] op_sel_hi:[1,0]
	v_mov_b64_e32 v[54:55], 0
	v_pk_mul_f32 v[144:145], v[20:21], v[166:167] op_sel_hi:[1,0]
	v_mov_b64_e32 v[20:21], 0
	v_mul_f32_e32 v133, 0xbfb8aa3b, v130
	v_exp_f32_e32 v133, v133
	v_pk_mul_f32 v[136:137], v[22:23], v[166:167] op_sel_hi:[1,0]
	v_mov_b64_e32 v[22:23], 0
	v_add_f32_e32 v133, 1.0, v133
	v_rcp_f32_e32 v134, v133
	v_mul_f32_e32 v133, 0xbfb8aa3b, v131
	v_exp_f32_e32 v133, v133
	s_nop 0
	v_add_f32_e32 v133, 1.0, v133
	v_rcp_f32_e32 v135, v133
	s_nop 0
	v_pk_mul_f32 v[130:131], v[130:131], v[134:135]
	v_pk_mul_f32 v[134:135], v[56:57], v[166:167] op_sel_hi:[1,0]
	v_mov_b64_e32 v[56:57], 0
	v_pk_mul_f32 v[130:131], v[136:137], v[130:131]
	v_mul_f32_e32 v133, 0xbfb8aa3b, v134
	v_exp_f32_e32 v133, v133
	s_nop 0
	v_add_f32_e32 v133, 1.0, v133
	v_rcp_f32_e32 v136, v133
	v_mul_f32_e32 v133, 0xbfb8aa3b, v135
	v_exp_f32_e32 v133, v133
	s_nop 0
	v_add_f32_e32 v133, 1.0, v133
	v_rcp_f32_e32 v137, v133
	s_nop 0
	v_pk_mul_f32 v[134:135], v[134:135], v[136:137]
	s_nop 0
	v_pk_mul_f32 v[136:137], v[140:141], v[134:135]
	v_pk_mul_f32 v[134:135], v[50:51], v[166:167] op_sel_hi:[1,0]
	v_mov_b64_e32 v[50:51], 0
	s_nop 0
	v_mul_f32_e32 v133, 0xbfb8aa3b, v134
	v_exp_f32_e32 v133, v133
	s_nop 0
	v_add_f32_e32 v133, 1.0, v133
	v_rcp_f32_e32 v140, v133
	v_mul_f32_e32 v133, 0xbfb8aa3b, v135
	v_exp_f32_e32 v133, v133
	s_nop 0
	v_add_f32_e32 v133, 1.0, v133
	v_rcp_f32_e32 v141, v133
	s_nop 0
	v_pk_mul_f32 v[134:135], v[134:135], v[140:141]
	s_nop 0
	v_pk_mul_f32 v[140:141], v[142:143], v[134:135]
	v_pk_mul_f32 v[134:135], v[52:53], v[166:167] op_sel_hi:[1,0]
	v_mov_b64_e32 v[52:53], 0
	s_nop 0
	v_mul_f32_e32 v133, 0xbfb8aa3b, v134
	v_exp_f32_e32 v133, v133
	s_nop 0
	v_add_f32_e32 v133, 1.0, v133
	v_rcp_f32_e32 v142, v133
	v_mul_f32_e32 v133, 0xbfb8aa3b, v135
	v_exp_f32_e32 v133, v133
	s_nop 0
	v_add_f32_e32 v133, 1.0, v133
	v_rcp_f32_e32 v143, v133
	s_nop 0
	v_pk_mul_f32 v[134:135], v[134:135], v[142:143]
	s_nop 0
	v_pk_mul_f32 v[142:143], v[144:145], v[134:135]
	v_cvt_pk_bf16_f32 v134, v130, v131
	v_cvt_pk_bf16_f32 v135, v136, v137
	v_cvt_pk_bf16_f32 v136, v140, v141
	v_cvt_pk_bf16_f32 v137, v142, v143
	v_lshl_add_u64 v[130:131], s[46:47], 0, v[156:157]
	global_store_dwordx4 v[130:131], v[134:137], off
	v_pk_mul_f32 v[130:131], v[46:47], v[132:133] op_sel_hi:[1,0]
	v_mov_b64_e32 v[46:47], 0
	s_nop 0
	v_mul_f32_e32 v133, 0xbfb8aa3b, v130
	v_exp_f32_e32 v133, v133
	s_nop 0
	v_add_f32_e32 v133, 1.0, v133
	v_rcp_f32_e32 v134, v133
	v_pk_mul_f32 v[136:137], v[14:15], v[132:133] op_sel_hi:[1,0]
	v_mov_b64_e32 v[14:15], 0
	v_mul_f32_e32 v133, 0xbfb8aa3b, v131
	v_exp_f32_e32 v133, v133
	s_nop 0
	v_add_f32_e32 v133, 1.0, v133
	v_rcp_f32_e32 v135, v133
	s_nop 0
	v_pk_mul_f32 v[130:131], v[130:131], v[134:135]
	v_pk_mul_f32 v[134:135], v[48:49], v[132:133] op_sel_hi:[1,0]
	v_mov_b64_e32 v[48:49], 0
	v_pk_mul_f32 v[130:131], v[136:137], v[130:131]
; __device__ __forceinline__ unsigned pk2(float lo, float hi) { f32x2_t v = {lo, hi}; bf16x2_t b = __builtin_convertvector(v, bf16x2_t); return __builtin_bit_cast(unsigned, b); }
; __device__ __forceinline__ float siluf_(float x) { return x * sigmoidf_(x); }
; #define PG8_BAR __builtin_amdgcn_s_barrier()
;     __device__ __forceinline__ void operator()(Acc& acc, const Unit& u, int wr, int wc, int fr, int fq, const float (&rsa)[2][4]) const {
;     ...
;             for (int m = 0; m < 4; ++m) {
;                 const int row = row0 + ai * HALF + m * 16; const float rs = rsa[ai][m];
;                 float o[8];
; #pragma unroll
;                 for (int n = 0; n < 2; ++n)
; #pragma unroll
;                     for (int j = 0; j < 4; ++j) { const float g = acc[ai][0][m][n][j] * rs, up = acc[ai][1][m][n][j] * rs; o[n * 4 + j] = siluf_(g) * up; }
;                 u32x4 w; w.x = pk2(o[0], o[1]); w.y = pk2(o[2], o[3]); w.z = pk2(o[4], o[5]); w.w = pk2(o[6], o[7]);
;                 const int rr = row & (BM - 1);
;                 *(u32x4*)((char*)O + ((size_t)(u.pm * (FF / BK) + (col0 >> 6))) * (2 * HTB) + (rr >> 7) * HTB + lds_byte(rr & 127, col0 & 63)) = w;
;             }
; template <class Epi, bool ALIGN_EPI, bool ABLK = false>
; __device__ __forceinline__ void gemm_phase(PG8_LAS unsigned char* lds, const Gemm g, const StaticOrder& S, const Epi& E) {
;     ...
;         if (!has_next) break;
;         if (!E.keep(cur)) {
; #pragma unroll
;             for (int a = 0; a < 2; ++a)
; #pragma unroll
;                 for (int b = 0; b < 2; ++b)
; #pragma unroll
;                     for (int m = 0; m < 4; ++m)
; #pragma unroll
;                         for (int n = 0; n < 2; ++n) acc[a][b][m][n] = (f32x4){0.f, 0.f, 0.f, 0.f};
;         }
;         cur = nxt; cA = nA; cB = nB; ++ui;
;         if constexpr (ALIGN_EPI) { if (wr == 1) PG8_BAR; }
	v_mul_f32_e32 v133, 0xbfb8aa3b, v134
	v_exp_f32_e32 v133, v133
	v_cvt_pk_bf16_f32 v130, v130, v131
	v_add_f32_e32 v133, 1.0, v133
	v_rcp_f32_e32 v136, v133
	v_pk_mul_f32 v[140:141], v[16:17], v[132:133] op_sel_hi:[1,0]
	v_mov_b64_e32 v[16:17], 0
	v_mul_f32_e32 v133, 0xbfb8aa3b, v135
	v_exp_f32_e32 v133, v133
	s_nop 0
	v_add_f32_e32 v133, 1.0, v133
	v_rcp_f32_e32 v137, v133
	s_nop 0
	v_pk_mul_f32 v[134:135], v[134:135], v[136:137]
	v_pk_mul_f32 v[136:137], v[42:43], v[132:133] op_sel_hi:[1,0]
	v_mov_b64_e32 v[42:43], 0
	v_pk_mul_f32 v[134:135], v[140:141], v[134:135]
	v_mul_f32_e32 v133, 0xbfb8aa3b, v136
	v_exp_f32_e32 v133, v133
	v_cvt_pk_bf16_f32 v131, v134, v135
	v_lshl_add_u64 v[134:135], s[46:47], 0, v[158:159]
	v_add_f32_e32 v133, 1.0, v133
	v_rcp_f32_e32 v140, v133
	v_pk_mul_f32 v[142:143], v[10:11], v[132:133] op_sel_hi:[1,0]
	v_mov_b64_e32 v[10:11], 0
	v_mul_f32_e32 v133, 0xbfb8aa3b, v137
	v_exp_f32_e32 v133, v133
	s_nop 0
	v_add_f32_e32 v133, 1.0, v133
	v_rcp_f32_e32 v141, v133
	s_nop 0
	v_pk_mul_f32 v[136:137], v[136:137], v[140:141]
	v_pk_mul_f32 v[140:141], v[44:45], v[132:133] op_sel_hi:[1,0]
	v_mov_b64_e32 v[44:45], 0
	v_pk_mul_f32 v[136:137], v[142:143], v[136:137]
	v_mul_f32_e32 v133, 0xbfb8aa3b, v140
	v_mul_f32_e32 v139, 0xbfb8aa3b, v141
	v_exp_f32_e32 v133, v133
	v_exp_f32_e32 v139, v139
	v_add_f32_e32 v133, 1.0, v133
	v_add_f32_e32 v139, 1.0, v139
	v_rcp_f32_e32 v142, v133
	v_rcp_f32_e32 v143, v139
	v_pk_mul_f32 v[132:133], v[12:13], v[132:133] op_sel_hi:[1,0]
	v_mov_b64_e32 v[12:13], 0
	v_pk_mul_f32 v[140:141], v[140:141], v[142:143]
	s_nop 0
	v_pk_mul_f32 v[140:141], v[132:133], v[140:141]
	v_cvt_pk_bf16_f32 v132, v136, v137
	v_cvt_pk_bf16_f32 v133, v140, v141
	global_store_dwordx4 v[134:135], v[130:133], off
	v_pk_mul_f32 v[134:135], v[6:7], v[138:139] op_sel_hi:[1,0]
	v_mov_b64_e32 v[6:7], 0
	v_pk_mul_f32 v[136:137], v[8:9], v[138:139] op_sel_hi:[1,0]
	v_mov_b64_e32 v[8:9], 0
	v_pk_mul_f32 v[130:131], v[38:39], v[138:139] op_sel_hi:[1,0]
	v_mov_b64_e32 v[38:39], 0
	v_pk_mul_f32 v[140:141], v[2:3], v[138:139] op_sel_hi:[1,0]
	v_mov_b64_e32 v[2:3], 0
	v_mul_f32_e32 v132, 0xbfb8aa3b, v130
	v_mul_f32_e32 v133, 0xbfb8aa3b, v131
	v_exp_f32_e32 v132, v132
	v_exp_f32_e32 v133, v133
	v_add_f32_e32 v132, 1.0, v132
	v_add_f32_e32 v133, 1.0, v133
	v_rcp_f32_e32 v132, v132
	v_rcp_f32_e32 v133, v133
	s_nop 0
	v_pk_mul_f32 v[130:131], v[130:131], v[132:133]
	v_pk_mul_f32 v[132:133], v[40:41], v[138:139] op_sel_hi:[1,0]
	v_mov_b64_e32 v[40:41], 0
	v_pk_mul_f32 v[130:131], v[134:135], v[130:131]
	v_mul_f32_e32 v134, 0xbfb8aa3b, v132
	v_mul_f32_e32 v135, 0xbfb8aa3b, v133
	v_exp_f32_e32 v134, v134
	v_exp_f32_e32 v135, v135
	v_cvt_pk_bf16_f32 v130, v130, v131
	v_add_f32_e32 v134, 1.0, v134
	v_add_f32_e32 v135, 1.0, v135
	v_rcp_f32_e32 v134, v134
	v_rcp_f32_e32 v135, v135
	s_nop 0
	v_pk_mul_f32 v[132:133], v[132:133], v[134:135]
	v_pk_mul_f32 v[134:135], v[34:35], v[138:139] op_sel_hi:[1,0]
	v_mov_b64_e32 v[34:35], 0
	v_pk_mul_f32 v[132:133], v[136:137], v[132:133]
	v_mul_f32_e32 v136, 0xbfb8aa3b, v134
	v_mul_f32_e32 v137, 0xbfb8aa3b, v135
	v_exp_f32_e32 v136, v136
	v_exp_f32_e32 v137, v137
	v_cvt_pk_bf16_f32 v131, v132, v133
	v_add_f32_e32 v136, 1.0, v136
	v_add_f32_e32 v137, 1.0, v137
	v_rcp_f32_e32 v136, v136
	v_rcp_f32_e32 v137, v137
	s_nop 0
	v_pk_mul_f32 v[134:135], v[134:135], v[136:137]
	v_pk_mul_f32 v[136:137], v[36:37], v[138:139] op_sel_hi:[1,0]
	v_mov_b64_e32 v[36:37], 0
	v_pk_mul_f32 v[134:135], v[140:141], v[134:135]
	v_mul_f32_e32 v139, 0xbfb8aa3b, v136
	v_mul_f32_e32 v141, 0xbfb8aa3b, v137
	v_exp_f32_e32 v139, v139
	v_exp_f32_e32 v141, v141
	v_cvt_pk_bf16_f32 v132, v134, v135
	v_lshl_add_u64 v[134:135], s[46:47], 0, v[160:161]
	v_add_f32_e32 v139, 1.0, v139
	v_add_f32_e32 v141, 1.0, v141
	v_rcp_f32_e32 v140, v139
	v_rcp_f32_e32 v141, v141
	v_pk_mul_f32 v[138:139], v[4:5], v[138:139] op_sel_hi:[1,0]
	v_mov_b64_e32 v[4:5], 0
	v_pk_mul_f32 v[136:137], v[136:137], v[140:141]
	s_nop 0
	v_pk_mul_f32 v[136:137], v[138:139], v[136:137]
	s_nop 0
	v_cvt_pk_bf16_f32 v133, v136, v137
	global_store_dwordx4 v[134:135], v[130:133], off
	s_cbranch_vccnz .LBB0_398
	s_andn2_b64 vcc, exec, s[26:27]
	s_cbranch_vccnz .Lp1_nz
	s_barrier
.Lp1_nz:
	s_mov_b32 s8, s40
	s_mov_b32 s10, s38
	s_mov_b64 s[22:23], s[44:45]
	s_mov_b64 s[24:25], s[42:43]
	s_mov_b32 s60, s33
	s_branch .LBB0_398

; __device__ __forceinline__ unsigned pk2(float lo, float hi) { f32x2_t v = {lo, hi}; bf16x2_t b = __builtin_convertvector(v, bf16x2_t); return __builtin_bit_cast(unsigned, b); }
; __device__ __forceinline__ float siluf_(float x) { return x * sigmoidf_(x); }
;     __device__ __forceinline__ void operator()(Acc& acc, const Unit& u, int wr, int wc, int fr, int fq, const float (&rsa)[2][4]) const {
;     ...
; #pragma unroll
;         for (int ai = 0; ai < 2; ++ai)
; #pragma unroll
;             for (int m = 0; m < 4; ++m) {
;                 const int row = u.pm * BM + ai * HALF + wr * 64 + m * 16 + fr; const float rs = rsa[ai][m] * scale;
; #pragma unroll
;                 for (int bj = 0; bj < 2; ++bj) {
;                     const int within = bj * HALF + wc * 32 + 8 * fq;
;                     f32x4 v0 = acc[ai][bj][m][0] * rs, v1 = acc[ai][bj][m][1] * rs;
;                     if (mode == 3) { if (within < GRANK) { *(f32x4*)(GLR + (size_t)row * 16 + within) = v0; *(f32x4*)(GLR + (size_t)row * 16 + within + 4) = v1; } continue; }
;                     if (mode == 1) {
; #pragma unroll
;                         for (int j = 0; j < 4; ++j) { v0[j] = siluf_(v0[j]); v1[j] = siluf_(v1[j]); }
;                     }
;                     u32x4 w; w.x = pk2(v0[0], v0[1]); w.y = pk2(v0[2], v0[3]); w.z = pk2(v1[0], v1[1]); w.w = pk2(v1[2], v1[3]);
;                     *(u32x4*)(dst + (size_t)row * ld + cbase + within) = w;
; template <class Epi, bool ALIGN_EPI, bool ABLK = false>
; __device__ __forceinline__ void gemm_phase(PG8_LAS unsigned char* lds, const Gemm g, const StaticOrder& S, const Epi& E) {
;     ...
;         if (!E.keep(cur)) {
; #pragma unroll
;             for (int a = 0; a < 2; ++a)
; #pragma unroll
;                 for (int b = 0; b < 2; ++b)
; #pragma unroll
;                     for (int m = 0; m < 4; ++m)
; #pragma unroll
;                         for (int n = 0; n < 2; ++n) acc[a][b][m][n] = (f32x4){0.f, 0.f, 0.f, 0.f};
;         }
.Lp3_fast:
	s_waitcnt lgkmcnt(0)
	v_readfirstlane_b32 s32, v0
	s_nop 3
	s_lshr_b32 s32, s32, 6
	s_lshr_b32 s79, s32, 2
	s_and_b32 s32, s32, 3
	s_lshl_b32 s86, s30, 8
	s_lshl_b32 s79, s79, 6
	s_add_u32 s86, s86, s79
	s_lshl_b32 s86, s86, 11
	s_and_b32 s79, s34, 3
	s_lshl_b32 s79, s79, 9
	s_lshl_b32 s32, s32, 6
	s_add_u32 s79, s79, s32
	s_add_u32 s86, s86, s79
	s_lshr_b32 s79, s34, 2
	s_mov_b32 s87, 0x7cc0000
	s_cmp_eq_u32 s79, 1
	s_cselect_b32 s87, 0xbd40000, s87
	s_cmp_eq_u32 s79, 2
	s_cselect_b32 s87, 0xfdc0000, s87
	s_cmp_eq_u32 s79, 3
	s_cselect_b32 s87, 0x17ec0000, s87
	s_add_u32 s86, s86, s87
	s_add_u32 s98, s96, s86
	s_addc_u32 s99, s97, 0
	s_mov_b32 s88, 1.0
	s_cmp_lt_u32 s34, 2
	s_cselect_b32 s88, 0x3db504f3, s88
	s_cmp_eq_u32 s79, 2
	s_cselect_b32 s88, 0x3e38aa3b, s88
	v_and_b32_e32 v222, 63, v0
	v_lshrrev_b32_e32 v223, 2, v222
	v_and_b32_e32 v222, 3, v222
	v_lshlrev_b32_e32 v220, 11, v223
	v_lshl_add_u32 v220, v222, 4, v220
	v_lshlrev_b32_e32 v221, 6, v222
	v_lshl_add_u32 v221, v223, 2, v221
	v_mul_f32_e32 v238, s88, v134
	v_pk_mul_f32 v[222:223], v[126:127], v[238:239] op_sel_hi:[1,0]
	v_mov_b64_e32 v[126:127], 0
	v_pk_mul_f32 v[224:225], v[128:129], v[238:239] op_sel_hi:[1,0]
	v_mov_b64_e32 v[128:129], 0
	v_pk_mul_f32 v[226:227], v[122:123], v[238:239] op_sel_hi:[1,0]
	v_mov_b64_e32 v[122:123], 0
	v_pk_mul_f32 v[228:229], v[124:125], v[238:239] op_sel_hi:[1,0]
	v_mov_b64_e32 v[124:125], 0
	s_cmp_lg_u32 s79, 3
	s_cbranch_scc1 .Lp3f_ns0
	v_mul_f32_e32 v230, 0xbfb8aa3b, v222
	v_mul_f32_e32 v231, 0xbfb8aa3b, v223
	v_mul_f32_e32 v232, 0xbfb8aa3b, v224
	v_mul_f32_e32 v233, 0xbfb8aa3b, v225
	v_mul_f32_e32 v234, 0xbfb8aa3b, v226
	v_mul_f32_e32 v235, 0xbfb8aa3b, v227
	v_mul_f32_e32 v236, 0xbfb8aa3b, v228
	v_mul_f32_e32 v237, 0xbfb8aa3b, v229
	v_exp_f32_e32 v230, v230
	v_exp_f32_e32 v231, v231
	v_exp_f32_e32 v232, v232
	v_exp_f32_e32 v233, v233
	v_exp_f32_e32 v234, v234
	v_exp_f32_e32 v235, v235
	v_exp_f32_e32 v236, v236
	v_exp_f32_e32 v237, v237
	v_add_f32_e32 v230, 1.0, v230
	v_add_f32_e32 v231, 1.0, v231
	v_add_f32_e32 v232, 1.0, v232
	v_add_f32_e32 v233, 1.0, v233
	v_add_f32_e32 v234, 1.0, v234
	v_add_f32_e32 v235, 1.0, v235
	v_add_f32_e32 v236, 1.0, v236
	v_add_f32_e32 v237, 1.0, v237
	v_rcp_f32_e32 v230, v230
	v_rcp_f32_e32 v231, v231
	v_rcp_f32_e32 v232, v232
	v_rcp_f32_e32 v233, v233
	v_rcp_f32_e32 v234, v234
	v_rcp_f32_e32 v235, v235
	v_rcp_f32_e32 v236, v236
	v_rcp_f32_e32 v237, v237
	v_pk_mul_f32 v[222:223], v[222:223], v[230:231]
	v_pk_mul_f32 v[224:225], v[224:225], v[232:233]
	v_pk_mul_f32 v[226:227], v[226:227], v[234:235]
	v_pk_mul_f32 v[228:229], v[228:229], v[236:237]
.Lp3f_ns0:
	v_cvt_pk_bf16_f32 v240, v222, v223
	v_cvt_pk_bf16_f32 v241, v224, v225
	v_cvt_pk_bf16_f32 v242, v226, v227
	v_cvt_pk_bf16_f32 v243, v228, v229
	ds_bpermute_b32 v244, v221, v240
	ds_bpermute_b32 v245, v221, v241
	ds_bpermute_b32 v246, v221, v242
	ds_bpermute_b32 v247, v221, v243
	v_pk_mul_f32 v[222:223], v[94:95], v[238:239] op_sel_hi:[1,0]
	v_mov_b64_e32 v[94:95], 0
	v_pk_mul_f32 v[224:225], v[96:97], v[238:239] op_sel_hi:[1,0]
	v_mov_b64_e32 v[96:97], 0
	v_pk_mul_f32 v[226:227], v[90:91], v[238:239] op_sel_hi:[1,0]
	v_mov_b64_e32 v[90:91], 0
	v_pk_mul_f32 v[228:229], v[92:93], v[238:239] op_sel_hi:[1,0]
	v_mov_b64_e32 v[92:93], 0
	s_cmp_lg_u32 s79, 3
	s_cbranch_scc1 .Lp3f_ns1
	v_mul_f32_e32 v230, 0xbfb8aa3b, v222
	v_mul_f32_e32 v231, 0xbfb8aa3b, v223
	v_mul_f32_e32 v232, 0xbfb8aa3b, v224
	v_mul_f32_e32 v233, 0xbfb8aa3b, v225
	v_mul_f32_e32 v234, 0xbfb8aa3b, v226
	v_mul_f32_e32 v235, 0xbfb8aa3b, v227
	v_mul_f32_e32 v236, 0xbfb8aa3b, v228
	v_mul_f32_e32 v237, 0xbfb8aa3b, v229
	v_exp_f32_e32 v230, v230
	v_exp_f32_e32 v231, v231
	v_exp_f32_e32 v232, v232
	v_exp_f32_e32 v233, v233
	v_exp_f32_e32 v234, v234
	v_exp_f32_e32 v235, v235
	v_exp_f32_e32 v236, v236
	v_exp_f32_e32 v237, v237
	v_add_f32_e32 v230, 1.0, v230
	v_add_f32_e32 v231, 1.0, v231
	v_add_f32_e32 v232, 1.0, v232
	v_add_f32_e32 v233, 1.0, v233
	v_add_f32_e32 v234, 1.0, v234
	v_add_f32_e32 v235, 1.0, v235
	v_add_f32_e32 v236, 1.0, v236
	v_add_f32_e32 v237, 1.0, v237
	v_rcp_f32_e32 v230, v230
	v_rcp_f32_e32 v231, v231
	v_rcp_f32_e32 v232, v232
	v_rcp_f32_e32 v233, v233
	v_rcp_f32_e32 v234, v234
	v_rcp_f32_e32 v235, v235
	v_rcp_f32_e32 v236, v236
	v_rcp_f32_e32 v237, v237
	v_pk_mul_f32 v[222:223], v[222:223], v[230:231]
	v_pk_mul_f32 v[224:225], v[224:225], v[232:233]
	v_pk_mul_f32 v[226:227], v[226:227], v[234:235]
	v_pk_mul_f32 v[228:229], v[228:229], v[236:237]
.Lp3f_ns1:
	v_cvt_pk_bf16_f32 v240, v222, v223
	v_cvt_pk_bf16_f32 v241, v224, v225
	v_cvt_pk_bf16_f32 v242, v226, v227
	v_cvt_pk_bf16_f32 v243, v228, v229
	ds_bpermute_b32 v248, v221, v240
	ds_bpermute_b32 v249, v221, v241
	ds_bpermute_b32 v250, v221, v242
	ds_bpermute_b32 v251, v221, v243
	s_waitcnt lgkmcnt(4)
	s_add_u32 s100, s98, 0x0
	s_addc_u32 s101, s99, 0
	global_store_dwordx4 v220, v[244:247], s[100:101] offset:0
	v_mul_f32_e32 v238, s88, v135
	v_pk_mul_f32 v[222:223], v[118:119], v[238:239] op_sel_hi:[1,0]
	v_mov_b64_e32 v[118:119], 0
	v_pk_mul_f32 v[224:225], v[120:121], v[238:239] op_sel_hi:[1,0]
	v_mov_b64_e32 v[120:121], 0
	v_pk_mul_f32 v[226:227], v[114:115], v[238:239] op_sel_hi:[1,0]
	v_mov_b64_e32 v[114:115], 0
	v_pk_mul_f32 v[228:229], v[116:117], v[238:239] op_sel_hi:[1,0]
	v_mov_b64_e32 v[116:117], 0
	s_cmp_lg_u32 s79, 3
	s_cbranch_scc1 .Lp3f_ns2
	v_mul_f32_e32 v230, 0xbfb8aa3b, v222
	v_mul_f32_e32 v231, 0xbfb8aa3b, v223
	v_mul_f32_e32 v232, 0xbfb8aa3b, v224
	v_mul_f32_e32 v233, 0xbfb8aa3b, v225
	v_mul_f32_e32 v234, 0xbfb8aa3b, v226
	v_mul_f32_e32 v235, 0xbfb8aa3b, v227
	v_mul_f32_e32 v236, 0xbfb8aa3b, v228
	v_mul_f32_e32 v237, 0xbfb8aa3b, v229
	v_exp_f32_e32 v230, v230
	v_exp_f32_e32 v231, v231
	v_exp_f32_e32 v232, v232
	v_exp_f32_e32 v233, v233
	v_exp_f32_e32 v234, v234
	v_exp_f32_e32 v235, v235
	v_exp_f32_e32 v236, v236
	v_exp_f32_e32 v237, v237
	v_add_f32_e32 v230, 1.0, v230
	v_add_f32_e32 v231, 1.0, v231
	v_add_f32_e32 v232, 1.0, v232
	v_add_f32_e32 v233, 1.0, v233
	v_add_f32_e32 v234, 1.0, v234
	v_add_f32_e32 v235, 1.0, v235
	v_add_f32_e32 v236, 1.0, v236
	v_add_f32_e32 v237, 1.0, v237
	v_rcp_f32_e32 v230, v230
	v_rcp_f32_e32 v231, v231
	v_rcp_f32_e32 v232, v232
	v_rcp_f32_e32 v233, v233
	v_rcp_f32_e32 v234, v234
	v_rcp_f32_e32 v235, v235
	v_rcp_f32_e32 v236, v236
	v_rcp_f32_e32 v237, v237
	v_pk_mul_f32 v[222:223], v[222:223], v[230:231]
	v_pk_mul_f32 v[224:225], v[224:225], v[232:233]
	v_pk_mul_f32 v[226:227], v[226:227], v[234:235]
	v_pk_mul_f32 v[228:229], v[228:229], v[236:237]
; __device__ __forceinline__ unsigned pk2(float lo, float hi) { f32x2_t v = {lo, hi}; bf16x2_t b = __builtin_convertvector(v, bf16x2_t); return __builtin_bit_cast(unsigned, b); }
; __device__ __forceinline__ float siluf_(float x) { return x * sigmoidf_(x); }
;     __device__ __forceinline__ void operator()(Acc& acc, const Unit& u, int wr, int wc, int fr, int fq, const float (&rsa)[2][4]) const {
;     ...
; #pragma unroll
;         for (int ai = 0; ai < 2; ++ai)
; #pragma unroll
;             for (int m = 0; m < 4; ++m) {
;                 const int row = u.pm * BM + ai * HALF + wr * 64 + m * 16 + fr; const float rs = rsa[ai][m] * scale;
; #pragma unroll
;                 for (int bj = 0; bj < 2; ++bj) {
;                     const int within = bj * HALF + wc * 32 + 8 * fq;
;                     f32x4 v0 = acc[ai][bj][m][0] * rs, v1 = acc[ai][bj][m][1] * rs;
;                     if (mode == 3) { if (within < GRANK) { *(f32x4*)(GLR + (size_t)row * 16 + within) = v0; *(f32x4*)(GLR + (size_t)row * 16 + within + 4) = v1; } continue; }
;                     if (mode == 1) {
; #pragma unroll
;                         for (int j = 0; j < 4; ++j) { v0[j] = siluf_(v0[j]); v1[j] = siluf_(v1[j]); }
;                     }
;                     u32x4 w; w.x = pk2(v0[0], v0[1]); w.y = pk2(v0[2], v0[3]); w.z = pk2(v1[0], v1[1]); w.w = pk2(v1[2], v1[3]);
;                     *(u32x4*)(dst + (size_t)row * ld + cbase + within) = w;
; template <class Epi, bool ALIGN_EPI, bool ABLK = false>
; __device__ __forceinline__ void gemm_phase(PG8_LAS unsigned char* lds, const Gemm g, const StaticOrder& S, const Epi& E) {
;     ...
;         if (!E.keep(cur)) {
; #pragma unroll
;             for (int a = 0; a < 2; ++a)
; #pragma unroll
;                 for (int b = 0; b < 2; ++b)
; #pragma unroll
;                     for (int m = 0; m < 4; ++m)
; #pragma unroll
;                         for (int n = 0; n < 2; ++n) acc[a][b][m][n] = (f32x4){0.f, 0.f, 0.f, 0.f};
;         }
.Lp3f_ns2:
	v_cvt_pk_bf16_f32 v240, v222, v223
	v_cvt_pk_bf16_f32 v241, v224, v225
	v_cvt_pk_bf16_f32 v242, v226, v227
	v_cvt_pk_bf16_f32 v243, v228, v229
	ds_bpermute_b32 v244, v221, v240
	ds_bpermute_b32 v245, v221, v241
	ds_bpermute_b32 v246, v221, v242
	ds_bpermute_b32 v247, v221, v243
	s_waitcnt lgkmcnt(4)
	s_add_u32 s100, s98, 0x0
	s_addc_u32 s101, s99, 0
	global_store_dwordx4 v220, v[248:251], s[100:101] offset:256
	v_pk_mul_f32 v[222:223], v[86:87], v[238:239] op_sel_hi:[1,0]
	v_mov_b64_e32 v[86:87], 0
	v_pk_mul_f32 v[224:225], v[88:89], v[238:239] op_sel_hi:[1,0]
	v_mov_b64_e32 v[88:89], 0
	v_pk_mul_f32 v[226:227], v[82:83], v[238:239] op_sel_hi:[1,0]
	v_mov_b64_e32 v[82:83], 0
	v_pk_mul_f32 v[228:229], v[84:85], v[238:239] op_sel_hi:[1,0]
	v_mov_b64_e32 v[84:85], 0
	s_cmp_lg_u32 s79, 3
	s_cbranch_scc1 .Lp3f_ns3
	v_mul_f32_e32 v230, 0xbfb8aa3b, v222
	v_mul_f32_e32 v231, 0xbfb8aa3b, v223
	v_mul_f32_e32 v232, 0xbfb8aa3b, v224
	v_mul_f32_e32 v233, 0xbfb8aa3b, v225
	v_mul_f32_e32 v234, 0xbfb8aa3b, v226
	v_mul_f32_e32 v235, 0xbfb8aa3b, v227
	v_mul_f32_e32 v236, 0xbfb8aa3b, v228
	v_mul_f32_e32 v237, 0xbfb8aa3b, v229
	v_exp_f32_e32 v230, v230
	v_exp_f32_e32 v231, v231
	v_exp_f32_e32 v232, v232
	v_exp_f32_e32 v233, v233
	v_exp_f32_e32 v234, v234
	v_exp_f32_e32 v235, v235
	v_exp_f32_e32 v236, v236
	v_exp_f32_e32 v237, v237
	v_add_f32_e32 v230, 1.0, v230
	v_add_f32_e32 v231, 1.0, v231
	v_add_f32_e32 v232, 1.0, v232
	v_add_f32_e32 v233, 1.0, v233
	v_add_f32_e32 v234, 1.0, v234
	v_add_f32_e32 v235, 1.0, v235
	v_add_f32_e32 v236, 1.0, v236
	v_add_f32_e32 v237, 1.0, v237
	v_rcp_f32_e32 v230, v230
	v_rcp_f32_e32 v231, v231
	v_rcp_f32_e32 v232, v232
	v_rcp_f32_e32 v233, v233
	v_rcp_f32_e32 v234, v234
	v_rcp_f32_e32 v235, v235
	v_rcp_f32_e32 v236, v236
	v_rcp_f32_e32 v237, v237
	v_pk_mul_f32 v[222:223], v[222:223], v[230:231]
	v_pk_mul_f32 v[224:225], v[224:225], v[232:233]
	v_pk_mul_f32 v[226:227], v[226:227], v[234:235]
	v_pk_mul_f32 v[228:229], v[228:229], v[236:237]
.Lp3f_ns3:
	v_cvt_pk_bf16_f32 v240, v222, v223
	v_cvt_pk_bf16_f32 v241, v224, v225
	v_cvt_pk_bf16_f32 v242, v226, v227
	v_cvt_pk_bf16_f32 v243, v228, v229
	ds_bpermute_b32 v248, v221, v240
	ds_bpermute_b32 v249, v221, v241
	ds_bpermute_b32 v250, v221, v242
	ds_bpermute_b32 v251, v221, v243
	s_waitcnt lgkmcnt(4)
	s_add_u32 s100, s98, 0x8000
	s_addc_u32 s101, s99, 0
	global_store_dwordx4 v220, v[244:247], s[100:101] offset:0
	v_mul_f32_e32 v238, s88, v136
	v_pk_mul_f32 v[222:223], v[110:111], v[238:239] op_sel_hi:[1,0]
	v_mov_b64_e32 v[110:111], 0
	v_pk_mul_f32 v[224:225], v[112:113], v[238:239] op_sel_hi:[1,0]
	v_mov_b64_e32 v[112:113], 0
	v_pk_mul_f32 v[226:227], v[106:107], v[238:239] op_sel_hi:[1,0]
	v_mov_b64_e32 v[106:107], 0
	v_pk_mul_f32 v[228:229], v[108:109], v[238:239] op_sel_hi:[1,0]
	v_mov_b64_e32 v[108:109], 0
	s_cmp_lg_u32 s79, 3
	s_cbranch_scc1 .Lp3f_ns4
	v_mul_f32_e32 v230, 0xbfb8aa3b, v222
	v_mul_f32_e32 v231, 0xbfb8aa3b, v223
	v_mul_f32_e32 v232, 0xbfb8aa3b, v224
	v_mul_f32_e32 v233, 0xbfb8aa3b, v225
	v_mul_f32_e32 v234, 0xbfb8aa3b, v226
	v_mul_f32_e32 v235, 0xbfb8aa3b, v227
	v_mul_f32_e32 v236, 0xbfb8aa3b, v228
	v_mul_f32_e32 v237, 0xbfb8aa3b, v229
	v_exp_f32_e32 v230, v230
	v_exp_f32_e32 v231, v231
	v_exp_f32_e32 v232, v232
	v_exp_f32_e32 v233, v233
	v_exp_f32_e32 v234, v234
	v_exp_f32_e32 v235, v235
	v_exp_f32_e32 v236, v236
	v_exp_f32_e32 v237, v237
	v_add_f32_e32 v230, 1.0, v230
	v_add_f32_e32 v231, 1.0, v231
	v_add_f32_e32 v232, 1.0, v232
	v_add_f32_e32 v233, 1.0, v233
	v_add_f32_e32 v234, 1.0, v234
	v_add_f32_e32 v235, 1.0, v235
	v_add_f32_e32 v236, 1.0, v236
	v_add_f32_e32 v237, 1.0, v237
	v_rcp_f32_e32 v230, v230
	v_rcp_f32_e32 v231, v231
	v_rcp_f32_e32 v232, v232
	v_rcp_f32_e32 v233, v233
	v_rcp_f32_e32 v234, v234
	v_rcp_f32_e32 v235, v235
	v_rcp_f32_e32 v236, v236
	v_rcp_f32_e32 v237, v237
	v_pk_mul_f32 v[222:223], v[222:223], v[230:231]
	v_pk_mul_f32 v[224:225], v[224:225], v[232:233]
	v_pk_mul_f32 v[226:227], v[226:227], v[234:235]
	v_pk_mul_f32 v[228:229], v[228:229], v[236:237]
.Lp3f_ns4:
	v_cvt_pk_bf16_f32 v240, v222, v223
	v_cvt_pk_bf16_f32 v241, v224, v225
	v_cvt_pk_bf16_f32 v242, v226, v227
	v_cvt_pk_bf16_f32 v243, v228, v229
	ds_bpermute_b32 v244, v221, v240
	ds_bpermute_b32 v245, v221, v241
	ds_bpermute_b32 v246, v221, v242
	ds_bpermute_b32 v247, v221, v243
	s_waitcnt lgkmcnt(4)
	s_add_u32 s100, s98, 0x8000
	s_addc_u32 s101, s99, 0
	global_store_dwordx4 v220, v[248:251], s[100:101] offset:256
	v_pk_mul_f32 v[222:223], v[78:79], v[238:239] op_sel_hi:[1,0]
	v_mov_b64_e32 v[78:79], 0
	v_pk_mul_f32 v[224:225], v[80:81], v[238:239] op_sel_hi:[1,0]
	v_mov_b64_e32 v[80:81], 0
	v_pk_mul_f32 v[226:227], v[74:75], v[238:239] op_sel_hi:[1,0]
	v_mov_b64_e32 v[74:75], 0
	v_pk_mul_f32 v[228:229], v[76:77], v[238:239] op_sel_hi:[1,0]
	v_mov_b64_e32 v[76:77], 0
	s_cmp_lg_u32 s79, 3
	s_cbranch_scc1 .Lp3f_ns5
	v_mul_f32_e32 v230, 0xbfb8aa3b, v222
	v_mul_f32_e32 v231, 0xbfb8aa3b, v223
	v_mul_f32_e32 v232, 0xbfb8aa3b, v224
	v_mul_f32_e32 v233, 0xbfb8aa3b, v225
	v_mul_f32_e32 v234, 0xbfb8aa3b, v226
	v_mul_f32_e32 v235, 0xbfb8aa3b, v227
	v_mul_f32_e32 v236, 0xbfb8aa3b, v228
	v_mul_f32_e32 v237, 0xbfb8aa3b, v229
	v_exp_f32_e32 v230, v230
	v_exp_f32_e32 v231, v231
	v_exp_f32_e32 v232, v232
	v_exp_f32_e32 v233, v233
	v_exp_f32_e32 v234, v234
	v_exp_f32_e32 v235, v235
	v_exp_f32_e32 v236, v236
	v_exp_f32_e32 v237, v237
	v_add_f32_e32 v230, 1.0, v230
	v_add_f32_e32 v231, 1.0, v231
	v_add_f32_e32 v232, 1.0, v232
	v_add_f32_e32 v233, 1.0, v233
	v_add_f32_e32 v234, 1.0, v234
	v_add_f32_e32 v235, 1.0, v235
	v_add_f32_e32 v236, 1.0, v236
	v_add_f32_e32 v237, 1.0, v237
	v_rcp_f32_e32 v230, v230
	v_rcp_f32_e32 v231, v231
	v_rcp_f32_e32 v232, v232
	v_rcp_f32_e32 v233, v233
	v_rcp_f32_e32 v234, v234
	v_rcp_f32_e32 v235, v235
	v_rcp_f32_e32 v236, v236
	v_rcp_f32_e32 v237, v237
	v_pk_mul_f32 v[222:223], v[222:223], v[230:231]
	v_pk_mul_f32 v[224:225], v[224:225], v[232:233]
	v_pk_mul_f32 v[226:227], v[226:227], v[234:235]
	v_pk_mul_f32 v[228:229], v[228:229], v[236:237]
; __device__ __forceinline__ unsigned pk2(float lo, float hi) { f32x2_t v = {lo, hi}; bf16x2_t b = __builtin_convertvector(v, bf16x2_t); return __builtin_bit_cast(unsigned, b); }
; __device__ __forceinline__ float siluf_(float x) { return x * sigmoidf_(x); }
;     __device__ __forceinline__ void operator()(Acc& acc, const Unit& u, int wr, int wc, int fr, int fq, const float (&rsa)[2][4]) const {
;     ...
;                 const int row = u.pm * BM + ai * HALF + wr * 64 + m * 16 + fr; const float rs = rsa[ai][m] * scale;
; #pragma unroll
;                 for (int bj = 0; bj < 2; ++bj) {
;                     const int within = bj * HALF + wc * 32 + 8 * fq;
;                     f32x4 v0 = acc[ai][bj][m][0] * rs, v1 = acc[ai][bj][m][1] * rs;
;                     if (mode == 3) { if (within < GRANK) { *(f32x4*)(GLR + (size_t)row * 16 + within) = v0; *(f32x4*)(GLR + (size_t)row * 16 + within + 4) = v1; } continue; }
;                     if (mode == 1) {
; #pragma unroll
;                         for (int j = 0; j < 4; ++j) { v0[j] = siluf_(v0[j]); v1[j] = siluf_(v1[j]); }
;                     }
;                     u32x4 w; w.x = pk2(v0[0], v0[1]); w.y = pk2(v0[2], v0[3]); w.z = pk2(v1[0], v1[1]); w.w = pk2(v1[2], v1[3]);
;                     *(u32x4*)(dst + (size_t)row * ld + cbase + within) = w;
; template <class Epi, bool ALIGN_EPI, bool ABLK = false>
; __device__ __forceinline__ void gemm_phase(PG8_LAS unsigned char* lds, const Gemm g, const StaticOrder& S, const Epi& E) {
;     ...
;         if (!E.keep(cur)) {
; #pragma unroll
;             for (int a = 0; a < 2; ++a)
; #pragma unroll
;                 for (int b = 0; b < 2; ++b)
; #pragma unroll
;                     for (int m = 0; m < 4; ++m)
; #pragma unroll
;                         for (int n = 0; n < 2; ++n) acc[a][b][m][n] = (f32x4){0.f, 0.f, 0.f, 0.f};
;         }
.Lp3f_ns5:
	v_cvt_pk_bf16_f32 v240, v222, v223
	v_cvt_pk_bf16_f32 v241, v224, v225
	v_cvt_pk_bf16_f32 v242, v226, v227
	v_cvt_pk_bf16_f32 v243, v228, v229
	ds_bpermute_b32 v248, v221, v240
	ds_bpermute_b32 v249, v221, v241
	ds_bpermute_b32 v250, v221, v242
	ds_bpermute_b32 v251, v221, v243
	s_waitcnt lgkmcnt(4)
	s_add_u32 s100, s98, 0x10000
	s_addc_u32 s101, s99, 0
	global_store_dwordx4 v220, v[244:247], s[100:101] offset:0
	v_mul_f32_e32 v238, s88, v137
	v_pk_mul_f32 v[222:223], v[102:103], v[238:239] op_sel_hi:[1,0]
	v_mov_b64_e32 v[102:103], 0
	v_pk_mul_f32 v[224:225], v[104:105], v[238:239] op_sel_hi:[1,0]
	v_mov_b64_e32 v[104:105], 0
	v_pk_mul_f32 v[226:227], v[98:99], v[238:239] op_sel_hi:[1,0]
	v_mov_b64_e32 v[98:99], 0
	v_pk_mul_f32 v[228:229], v[100:101], v[238:239] op_sel_hi:[1,0]
	v_mov_b64_e32 v[100:101], 0
	s_cmp_lg_u32 s79, 3
	s_cbranch_scc1 .Lp3f_ns6
	v_mul_f32_e32 v230, 0xbfb8aa3b, v222
	v_mul_f32_e32 v231, 0xbfb8aa3b, v223
	v_mul_f32_e32 v232, 0xbfb8aa3b, v224
	v_mul_f32_e32 v233, 0xbfb8aa3b, v225
	v_mul_f32_e32 v234, 0xbfb8aa3b, v226
	v_mul_f32_e32 v235, 0xbfb8aa3b, v227
	v_mul_f32_e32 v236, 0xbfb8aa3b, v228
	v_mul_f32_e32 v237, 0xbfb8aa3b, v229
	v_exp_f32_e32 v230, v230
	v_exp_f32_e32 v231, v231
	v_exp_f32_e32 v232, v232
	v_exp_f32_e32 v233, v233
	v_exp_f32_e32 v234, v234
	v_exp_f32_e32 v235, v235
	v_exp_f32_e32 v236, v236
	v_exp_f32_e32 v237, v237
	v_add_f32_e32 v230, 1.0, v230
	v_add_f32_e32 v231, 1.0, v231
	v_add_f32_e32 v232, 1.0, v232
	v_add_f32_e32 v233, 1.0, v233
	v_add_f32_e32 v234, 1.0, v234
	v_add_f32_e32 v235, 1.0, v235
	v_add_f32_e32 v236, 1.0, v236
	v_add_f32_e32 v237, 1.0, v237
	v_rcp_f32_e32 v230, v230
	v_rcp_f32_e32 v231, v231
	v_rcp_f32_e32 v232, v232
	v_rcp_f32_e32 v233, v233
	v_rcp_f32_e32 v234, v234
	v_rcp_f32_e32 v235, v235
	v_rcp_f32_e32 v236, v236
	v_rcp_f32_e32 v237, v237
	v_pk_mul_f32 v[222:223], v[222:223], v[230:231]
	v_pk_mul_f32 v[224:225], v[224:225], v[232:233]
	v_pk_mul_f32 v[226:227], v[226:227], v[234:235]
	v_pk_mul_f32 v[228:229], v[228:229], v[236:237]
.Lp3f_ns6:
	v_cvt_pk_bf16_f32 v240, v222, v223
	v_cvt_pk_bf16_f32 v241, v224, v225
	v_cvt_pk_bf16_f32 v242, v226, v227
	v_cvt_pk_bf16_f32 v243, v228, v229
	ds_bpermute_b32 v244, v221, v240
	ds_bpermute_b32 v245, v221, v241
	ds_bpermute_b32 v246, v221, v242
	ds_bpermute_b32 v247, v221, v243
	s_waitcnt lgkmcnt(4)
	s_add_u32 s100, s98, 0x10000
	s_addc_u32 s101, s99, 0
	global_store_dwordx4 v220, v[248:251], s[100:101] offset:256
	v_pk_mul_f32 v[222:223], v[70:71], v[238:239] op_sel_hi:[1,0]
	v_mov_b64_e32 v[70:71], 0
	v_pk_mul_f32 v[224:225], v[72:73], v[238:239] op_sel_hi:[1,0]
	v_mov_b64_e32 v[72:73], 0
	v_pk_mul_f32 v[226:227], v[66:67], v[238:239] op_sel_hi:[1,0]
	v_mov_b64_e32 v[66:67], 0
	v_pk_mul_f32 v[228:229], v[68:69], v[238:239] op_sel_hi:[1,0]
	v_mov_b64_e32 v[68:69], 0
	s_cmp_lg_u32 s79, 3
	s_cbranch_scc1 .Lp3f_ns7
	v_mul_f32_e32 v230, 0xbfb8aa3b, v222
	v_mul_f32_e32 v231, 0xbfb8aa3b, v223
	v_mul_f32_e32 v232, 0xbfb8aa3b, v224
	v_mul_f32_e32 v233, 0xbfb8aa3b, v225
	v_mul_f32_e32 v234, 0xbfb8aa3b, v226
	v_mul_f32_e32 v235, 0xbfb8aa3b, v227
	v_mul_f32_e32 v236, 0xbfb8aa3b, v228
	v_mul_f32_e32 v237, 0xbfb8aa3b, v229
	v_exp_f32_e32 v230, v230
	v_exp_f32_e32 v231, v231
	v_exp_f32_e32 v232, v232
	v_exp_f32_e32 v233, v233
	v_exp_f32_e32 v234, v234
	v_exp_f32_e32 v235, v235
	v_exp_f32_e32 v236, v236
	v_exp_f32_e32 v237, v237
	v_add_f32_e32 v230, 1.0, v230
	v_add_f32_e32 v231, 1.0, v231
	v_add_f32_e32 v232, 1.0, v232
	v_add_f32_e32 v233, 1.0, v233
	v_add_f32_e32 v234, 1.0, v234
	v_add_f32_e32 v235, 1.0, v235
	v_add_f32_e32 v236, 1.0, v236
	v_add_f32_e32 v237, 1.0, v237
	v_rcp_f32_e32 v230, v230
	v_rcp_f32_e32 v231, v231
	v_rcp_f32_e32 v232, v232
	v_rcp_f32_e32 v233, v233
	v_rcp_f32_e32 v234, v234
	v_rcp_f32_e32 v235, v235
	v_rcp_f32_e32 v236, v236
	v_rcp_f32_e32 v237, v237
	v_pk_mul_f32 v[222:223], v[222:223], v[230:231]
	v_pk_mul_f32 v[224:225], v[224:225], v[232:233]
	v_pk_mul_f32 v[226:227], v[226:227], v[234:235]
	v_pk_mul_f32 v[228:229], v[228:229], v[236:237]
.Lp3f_ns7:
	v_cvt_pk_bf16_f32 v240, v222, v223
	v_cvt_pk_bf16_f32 v241, v224, v225
	v_cvt_pk_bf16_f32 v242, v226, v227
	v_cvt_pk_bf16_f32 v243, v228, v229
	ds_bpermute_b32 v248, v221, v240
	ds_bpermute_b32 v249, v221, v241
	ds_bpermute_b32 v250, v221, v242
	ds_bpermute_b32 v251, v221, v243
	s_waitcnt lgkmcnt(4)
	s_add_u32 s100, s98, 0x18000
	s_addc_u32 s101, s99, 0
	global_store_dwordx4 v220, v[244:247], s[100:101] offset:0
	v_mul_f32_e32 v238, s88, v130
	v_pk_mul_f32 v[222:223], v[62:63], v[238:239] op_sel_hi:[1,0]
	v_mov_b64_e32 v[62:63], 0
	v_pk_mul_f32 v[224:225], v[64:65], v[238:239] op_sel_hi:[1,0]
	v_mov_b64_e32 v[64:65], 0
	v_pk_mul_f32 v[226:227], v[58:59], v[238:239] op_sel_hi:[1,0]
	v_mov_b64_e32 v[58:59], 0
	v_pk_mul_f32 v[228:229], v[60:61], v[238:239] op_sel_hi:[1,0]
	v_mov_b64_e32 v[60:61], 0
	s_cmp_lg_u32 s79, 3
	s_cbranch_scc1 .Lp3f_ns8
	v_mul_f32_e32 v230, 0xbfb8aa3b, v222
	v_mul_f32_e32 v231, 0xbfb8aa3b, v223
	v_mul_f32_e32 v232, 0xbfb8aa3b, v224
	v_mul_f32_e32 v233, 0xbfb8aa3b, v225
	v_mul_f32_e32 v234, 0xbfb8aa3b, v226
	v_mul_f32_e32 v235, 0xbfb8aa3b, v227
	v_mul_f32_e32 v236, 0xbfb8aa3b, v228
	v_mul_f32_e32 v237, 0xbfb8aa3b, v229
	v_exp_f32_e32 v230, v230
	v_exp_f32_e32 v231, v231
	v_exp_f32_e32 v232, v232
	v_exp_f32_e32 v233, v233
	v_exp_f32_e32 v234, v234
	v_exp_f32_e32 v235, v235
	v_exp_f32_e32 v236, v236
	v_exp_f32_e32 v237, v237
	v_add_f32_e32 v230, 1.0, v230
	v_add_f32_e32 v231, 1.0, v231
	v_add_f32_e32 v232, 1.0, v232
	v_add_f32_e32 v233, 1.0, v233
	v_add_f32_e32 v234, 1.0, v234
	v_add_f32_e32 v235, 1.0, v235
	v_add_f32_e32 v236, 1.0, v236
	v_add_f32_e32 v237, 1.0, v237
	v_rcp_f32_e32 v230, v230
	v_rcp_f32_e32 v231, v231
	v_rcp_f32_e32 v232, v232
	v_rcp_f32_e32 v233, v233
	v_rcp_f32_e32 v234, v234
	v_rcp_f32_e32 v235, v235
	v_rcp_f32_e32 v236, v236
	v_rcp_f32_e32 v237, v237
	v_pk_mul_f32 v[222:223], v[222:223], v[230:231]
	v_pk_mul_f32 v[224:225], v[224:225], v[232:233]
	v_pk_mul_f32 v[226:227], v[226:227], v[234:235]
	v_pk_mul_f32 v[228:229], v[228:229], v[236:237]
; __device__ __forceinline__ unsigned pk2(float lo, float hi) { f32x2_t v = {lo, hi}; bf16x2_t b = __builtin_convertvector(v, bf16x2_t); return __builtin_bit_cast(unsigned, b); }
; __device__ __forceinline__ float siluf_(float x) { return x * sigmoidf_(x); }
;     __device__ __forceinline__ void operator()(Acc& acc, const Unit& u, int wr, int wc, int fr, int fq, const float (&rsa)[2][4]) const {
;     ...
;                 const int row = u.pm * BM + ai * HALF + wr * 64 + m * 16 + fr; const float rs = rsa[ai][m] * scale;
; #pragma unroll
;                 for (int bj = 0; bj < 2; ++bj) {
;                     const int within = bj * HALF + wc * 32 + 8 * fq;
;                     f32x4 v0 = acc[ai][bj][m][0] * rs, v1 = acc[ai][bj][m][1] * rs;
;                     if (mode == 3) { if (within < GRANK) { *(f32x4*)(GLR + (size_t)row * 16 + within) = v0; *(f32x4*)(GLR + (size_t)row * 16 + within + 4) = v1; } continue; }
;                     if (mode == 1) {
; #pragma unroll
;                         for (int j = 0; j < 4; ++j) { v0[j] = siluf_(v0[j]); v1[j] = siluf_(v1[j]); }
;                     }
;                     u32x4 w; w.x = pk2(v0[0], v0[1]); w.y = pk2(v0[2], v0[3]); w.z = pk2(v1[0], v1[1]); w.w = pk2(v1[2], v1[3]);
;                     *(u32x4*)(dst + (size_t)row * ld + cbase + within) = w;
; template <class Epi, bool ALIGN_EPI, bool ABLK = false>
; __device__ __forceinline__ void gemm_phase(PG8_LAS unsigned char* lds, const Gemm g, const StaticOrder& S, const Epi& E) {
;     ...
;         if (!E.keep(cur)) {
; #pragma unroll
;             for (int a = 0; a < 2; ++a)
; #pragma unroll
;                 for (int b = 0; b < 2; ++b)
; #pragma unroll
;                     for (int m = 0; m < 4; ++m)
; #pragma unroll
;                         for (int n = 0; n < 2; ++n) acc[a][b][m][n] = (f32x4){0.f, 0.f, 0.f, 0.f};
;         }
.Lp3f_ns8:
	v_cvt_pk_bf16_f32 v240, v222, v223
	v_cvt_pk_bf16_f32 v241, v224, v225
	v_cvt_pk_bf16_f32 v242, v226, v227
	v_cvt_pk_bf16_f32 v243, v228, v229
	ds_bpermute_b32 v244, v221, v240
	ds_bpermute_b32 v245, v221, v241
	ds_bpermute_b32 v246, v221, v242
	ds_bpermute_b32 v247, v221, v243
	s_waitcnt lgkmcnt(4)
	s_add_u32 s100, s98, 0x18000
	s_addc_u32 s101, s99, 0
	global_store_dwordx4 v220, v[248:251], s[100:101] offset:256
	v_pk_mul_f32 v[222:223], v[30:31], v[238:239] op_sel_hi:[1,0]
	v_mov_b64_e32 v[30:31], 0
	v_pk_mul_f32 v[224:225], v[32:33], v[238:239] op_sel_hi:[1,0]
	v_mov_b64_e32 v[32:33], 0
	v_pk_mul_f32 v[226:227], v[26:27], v[238:239] op_sel_hi:[1,0]
	v_mov_b64_e32 v[26:27], 0
	v_pk_mul_f32 v[228:229], v[28:29], v[238:239] op_sel_hi:[1,0]
	v_mov_b64_e32 v[28:29], 0
	s_cmp_lg_u32 s79, 3
	s_cbranch_scc1 .Lp3f_ns9
	v_mul_f32_e32 v230, 0xbfb8aa3b, v222
	v_mul_f32_e32 v231, 0xbfb8aa3b, v223
	v_mul_f32_e32 v232, 0xbfb8aa3b, v224
	v_mul_f32_e32 v233, 0xbfb8aa3b, v225
	v_mul_f32_e32 v234, 0xbfb8aa3b, v226
	v_mul_f32_e32 v235, 0xbfb8aa3b, v227
	v_mul_f32_e32 v236, 0xbfb8aa3b, v228
	v_mul_f32_e32 v237, 0xbfb8aa3b, v229
	v_exp_f32_e32 v230, v230
	v_exp_f32_e32 v231, v231
	v_exp_f32_e32 v232, v232
	v_exp_f32_e32 v233, v233
	v_exp_f32_e32 v234, v234
	v_exp_f32_e32 v235, v235
	v_exp_f32_e32 v236, v236
	v_exp_f32_e32 v237, v237
	v_add_f32_e32 v230, 1.0, v230
	v_add_f32_e32 v231, 1.0, v231
	v_add_f32_e32 v232, 1.0, v232
	v_add_f32_e32 v233, 1.0, v233
	v_add_f32_e32 v234, 1.0, v234
	v_add_f32_e32 v235, 1.0, v235
	v_add_f32_e32 v236, 1.0, v236
	v_add_f32_e32 v237, 1.0, v237
	v_rcp_f32_e32 v230, v230
	v_rcp_f32_e32 v231, v231
	v_rcp_f32_e32 v232, v232
	v_rcp_f32_e32 v233, v233
	v_rcp_f32_e32 v234, v234
	v_rcp_f32_e32 v235, v235
	v_rcp_f32_e32 v236, v236
	v_rcp_f32_e32 v237, v237
	v_pk_mul_f32 v[222:223], v[222:223], v[230:231]
	v_pk_mul_f32 v[224:225], v[224:225], v[232:233]
	v_pk_mul_f32 v[226:227], v[226:227], v[234:235]
	v_pk_mul_f32 v[228:229], v[228:229], v[236:237]
.Lp3f_ns9:
	v_cvt_pk_bf16_f32 v240, v222, v223
	v_cvt_pk_bf16_f32 v241, v224, v225
	v_cvt_pk_bf16_f32 v242, v226, v227
	v_cvt_pk_bf16_f32 v243, v228, v229
	ds_bpermute_b32 v248, v221, v240
	ds_bpermute_b32 v249, v221, v241
	ds_bpermute_b32 v250, v221, v242
	ds_bpermute_b32 v251, v221, v243
	s_waitcnt lgkmcnt(4)
	s_add_u32 s100, s98, 0x40000
	s_addc_u32 s101, s99, 0
	global_store_dwordx4 v220, v[244:247], s[100:101] offset:0
	v_mul_f32_e32 v238, s88, v131
	v_pk_mul_f32 v[222:223], v[54:55], v[238:239] op_sel_hi:[1,0]
	v_mov_b64_e32 v[54:55], 0
	v_pk_mul_f32 v[224:225], v[56:57], v[238:239] op_sel_hi:[1,0]
	v_mov_b64_e32 v[56:57], 0
	v_pk_mul_f32 v[226:227], v[50:51], v[238:239] op_sel_hi:[1,0]
	v_mov_b64_e32 v[50:51], 0
	v_pk_mul_f32 v[228:229], v[52:53], v[238:239] op_sel_hi:[1,0]
	v_mov_b64_e32 v[52:53], 0
	s_cmp_lg_u32 s79, 3
	s_cbranch_scc1 .Lp3f_ns10
	v_mul_f32_e32 v230, 0xbfb8aa3b, v222
	v_mul_f32_e32 v231, 0xbfb8aa3b, v223
	v_mul_f32_e32 v232, 0xbfb8aa3b, v224
	v_mul_f32_e32 v233, 0xbfb8aa3b, v225
	v_mul_f32_e32 v234, 0xbfb8aa3b, v226
	v_mul_f32_e32 v235, 0xbfb8aa3b, v227
	v_mul_f32_e32 v236, 0xbfb8aa3b, v228
	v_mul_f32_e32 v237, 0xbfb8aa3b, v229
	v_exp_f32_e32 v230, v230
	v_exp_f32_e32 v231, v231
	v_exp_f32_e32 v232, v232
	v_exp_f32_e32 v233, v233
	v_exp_f32_e32 v234, v234
	v_exp_f32_e32 v235, v235
	v_exp_f32_e32 v236, v236
	v_exp_f32_e32 v237, v237
	v_add_f32_e32 v230, 1.0, v230
	v_add_f32_e32 v231, 1.0, v231
	v_add_f32_e32 v232, 1.0, v232
	v_add_f32_e32 v233, 1.0, v233
	v_add_f32_e32 v234, 1.0, v234
	v_add_f32_e32 v235, 1.0, v235
	v_add_f32_e32 v236, 1.0, v236
	v_add_f32_e32 v237, 1.0, v237
	v_rcp_f32_e32 v230, v230
	v_rcp_f32_e32 v231, v231
	v_rcp_f32_e32 v232, v232
	v_rcp_f32_e32 v233, v233
	v_rcp_f32_e32 v234, v234
	v_rcp_f32_e32 v235, v235
	v_rcp_f32_e32 v236, v236
	v_rcp_f32_e32 v237, v237
	v_pk_mul_f32 v[222:223], v[222:223], v[230:231]
	v_pk_mul_f32 v[224:225], v[224:225], v[232:233]
	v_pk_mul_f32 v[226:227], v[226:227], v[234:235]
	v_pk_mul_f32 v[228:229], v[228:229], v[236:237]
.Lp3f_ns10:
	v_cvt_pk_bf16_f32 v240, v222, v223
	v_cvt_pk_bf16_f32 v241, v224, v225
	v_cvt_pk_bf16_f32 v242, v226, v227
	v_cvt_pk_bf16_f32 v243, v228, v229
	ds_bpermute_b32 v244, v221, v240
	ds_bpermute_b32 v245, v221, v241
	ds_bpermute_b32 v246, v221, v242
	ds_bpermute_b32 v247, v221, v243
	s_waitcnt lgkmcnt(4)
	s_add_u32 s100, s98, 0x40000
	s_addc_u32 s101, s99, 0
	global_store_dwordx4 v220, v[248:251], s[100:101] offset:256
	v_pk_mul_f32 v[222:223], v[22:23], v[238:239] op_sel_hi:[1,0]
	v_mov_b64_e32 v[22:23], 0
	v_pk_mul_f32 v[224:225], v[24:25], v[238:239] op_sel_hi:[1,0]
	v_mov_b64_e32 v[24:25], 0
	v_pk_mul_f32 v[226:227], v[18:19], v[238:239] op_sel_hi:[1,0]
	v_mov_b64_e32 v[18:19], 0
	v_pk_mul_f32 v[228:229], v[20:21], v[238:239] op_sel_hi:[1,0]
	v_mov_b64_e32 v[20:21], 0
	s_cmp_lg_u32 s79, 3
	s_cbranch_scc1 .Lp3f_ns11
	v_mul_f32_e32 v230, 0xbfb8aa3b, v222
	v_mul_f32_e32 v231, 0xbfb8aa3b, v223
	v_mul_f32_e32 v232, 0xbfb8aa3b, v224
	v_mul_f32_e32 v233, 0xbfb8aa3b, v225
	v_mul_f32_e32 v234, 0xbfb8aa3b, v226
	v_mul_f32_e32 v235, 0xbfb8aa3b, v227
	v_mul_f32_e32 v236, 0xbfb8aa3b, v228
	v_mul_f32_e32 v237, 0xbfb8aa3b, v229
	v_exp_f32_e32 v230, v230
	v_exp_f32_e32 v231, v231
	v_exp_f32_e32 v232, v232
	v_exp_f32_e32 v233, v233
	v_exp_f32_e32 v234, v234
	v_exp_f32_e32 v235, v235
	v_exp_f32_e32 v236, v236
	v_exp_f32_e32 v237, v237
	v_add_f32_e32 v230, 1.0, v230
	v_add_f32_e32 v231, 1.0, v231
	v_add_f32_e32 v232, 1.0, v232
	v_add_f32_e32 v233, 1.0, v233
	v_add_f32_e32 v234, 1.0, v234
	v_add_f32_e32 v235, 1.0, v235
	v_add_f32_e32 v236, 1.0, v236
	v_add_f32_e32 v237, 1.0, v237
	v_rcp_f32_e32 v230, v230
	v_rcp_f32_e32 v231, v231
	v_rcp_f32_e32 v232, v232
	v_rcp_f32_e32 v233, v233
	v_rcp_f32_e32 v234, v234
	v_rcp_f32_e32 v235, v235
	v_rcp_f32_e32 v236, v236
	v_rcp_f32_e32 v237, v237
	v_pk_mul_f32 v[222:223], v[222:223], v[230:231]
	v_pk_mul_f32 v[224:225], v[224:225], v[232:233]
	v_pk_mul_f32 v[226:227], v[226:227], v[234:235]
	v_pk_mul_f32 v[228:229], v[228:229], v[236:237]
; __device__ __forceinline__ unsigned pk2(float lo, float hi) { f32x2_t v = {lo, hi}; bf16x2_t b = __builtin_convertvector(v, bf16x2_t); return __builtin_bit_cast(unsigned, b); }
; __device__ __forceinline__ float siluf_(float x) { return x * sigmoidf_(x); }
;     __device__ __forceinline__ void operator()(Acc& acc, const Unit& u, int wr, int wc, int fr, int fq, const float (&rsa)[2][4]) const {
;     ...
;                 const int row = u.pm * BM + ai * HALF + wr * 64 + m * 16 + fr; const float rs = rsa[ai][m] * scale;
; #pragma unroll
;                 for (int bj = 0; bj < 2; ++bj) {
;                     const int within = bj * HALF + wc * 32 + 8 * fq;
;                     f32x4 v0 = acc[ai][bj][m][0] * rs, v1 = acc[ai][bj][m][1] * rs;
;                     if (mode == 3) { if (within < GRANK) { *(f32x4*)(GLR + (size_t)row * 16 + within) = v0; *(f32x4*)(GLR + (size_t)row * 16 + within + 4) = v1; } continue; }
;                     if (mode == 1) {
; #pragma unroll
;                         for (int j = 0; j < 4; ++j) { v0[j] = siluf_(v0[j]); v1[j] = siluf_(v1[j]); }
;                     }
;                     u32x4 w; w.x = pk2(v0[0], v0[1]); w.y = pk2(v0[2], v0[3]); w.z = pk2(v1[0], v1[1]); w.w = pk2(v1[2], v1[3]);
;                     *(u32x4*)(dst + (size_t)row * ld + cbase + within) = w;
; template <class Epi, bool ALIGN_EPI, bool ABLK = false>
; __device__ __forceinline__ void gemm_phase(PG8_LAS unsigned char* lds, const Gemm g, const StaticOrder& S, const Epi& E) {
;     ...
;         if (!E.keep(cur)) {
; #pragma unroll
;             for (int a = 0; a < 2; ++a)
; #pragma unroll
;                 for (int b = 0; b < 2; ++b)
; #pragma unroll
;                     for (int m = 0; m < 4; ++m)
; #pragma unroll
;                         for (int n = 0; n < 2; ++n) acc[a][b][m][n] = (f32x4){0.f, 0.f, 0.f, 0.f};
;         }
.Lp3f_ns11:
	v_cvt_pk_bf16_f32 v240, v222, v223
	v_cvt_pk_bf16_f32 v241, v224, v225
	v_cvt_pk_bf16_f32 v242, v226, v227
	v_cvt_pk_bf16_f32 v243, v228, v229
	ds_bpermute_b32 v248, v221, v240
	ds_bpermute_b32 v249, v221, v241
	ds_bpermute_b32 v250, v221, v242
	ds_bpermute_b32 v251, v221, v243
	s_waitcnt lgkmcnt(4)
	s_add_u32 s100, s98, 0x48000
	s_addc_u32 s101, s99, 0
	global_store_dwordx4 v220, v[244:247], s[100:101] offset:0
	v_mul_f32_e32 v238, s88, v132
	v_pk_mul_f32 v[222:223], v[46:47], v[238:239] op_sel_hi:[1,0]
	v_mov_b64_e32 v[46:47], 0
	v_pk_mul_f32 v[224:225], v[48:49], v[238:239] op_sel_hi:[1,0]
	v_mov_b64_e32 v[48:49], 0
	v_pk_mul_f32 v[226:227], v[42:43], v[238:239] op_sel_hi:[1,0]
	v_mov_b64_e32 v[42:43], 0
	v_pk_mul_f32 v[228:229], v[44:45], v[238:239] op_sel_hi:[1,0]
	v_mov_b64_e32 v[44:45], 0
	s_cmp_lg_u32 s79, 3
	s_cbranch_scc1 .Lp3f_ns12
	v_mul_f32_e32 v230, 0xbfb8aa3b, v222
	v_mul_f32_e32 v231, 0xbfb8aa3b, v223
	v_mul_f32_e32 v232, 0xbfb8aa3b, v224
	v_mul_f32_e32 v233, 0xbfb8aa3b, v225
	v_mul_f32_e32 v234, 0xbfb8aa3b, v226
	v_mul_f32_e32 v235, 0xbfb8aa3b, v227
	v_mul_f32_e32 v236, 0xbfb8aa3b, v228
	v_mul_f32_e32 v237, 0xbfb8aa3b, v229
	v_exp_f32_e32 v230, v230
	v_exp_f32_e32 v231, v231
	v_exp_f32_e32 v232, v232
	v_exp_f32_e32 v233, v233
	v_exp_f32_e32 v234, v234
	v_exp_f32_e32 v235, v235
	v_exp_f32_e32 v236, v236
	v_exp_f32_e32 v237, v237
	v_add_f32_e32 v230, 1.0, v230
	v_add_f32_e32 v231, 1.0, v231
	v_add_f32_e32 v232, 1.0, v232
	v_add_f32_e32 v233, 1.0, v233
	v_add_f32_e32 v234, 1.0, v234
	v_add_f32_e32 v235, 1.0, v235
	v_add_f32_e32 v236, 1.0, v236
	v_add_f32_e32 v237, 1.0, v237
	v_rcp_f32_e32 v230, v230
	v_rcp_f32_e32 v231, v231
	v_rcp_f32_e32 v232, v232
	v_rcp_f32_e32 v233, v233
	v_rcp_f32_e32 v234, v234
	v_rcp_f32_e32 v235, v235
	v_rcp_f32_e32 v236, v236
	v_rcp_f32_e32 v237, v237
	v_pk_mul_f32 v[222:223], v[222:223], v[230:231]
	v_pk_mul_f32 v[224:225], v[224:225], v[232:233]
	v_pk_mul_f32 v[226:227], v[226:227], v[234:235]
	v_pk_mul_f32 v[228:229], v[228:229], v[236:237]
.Lp3f_ns12:
	v_cvt_pk_bf16_f32 v240, v222, v223
	v_cvt_pk_bf16_f32 v241, v224, v225
	v_cvt_pk_bf16_f32 v242, v226, v227
	v_cvt_pk_bf16_f32 v243, v228, v229
	ds_bpermute_b32 v244, v221, v240
	ds_bpermute_b32 v245, v221, v241
	ds_bpermute_b32 v246, v221, v242
	ds_bpermute_b32 v247, v221, v243
	s_waitcnt lgkmcnt(4)
	s_add_u32 s100, s98, 0x48000
	s_addc_u32 s101, s99, 0
	global_store_dwordx4 v220, v[248:251], s[100:101] offset:256
	v_pk_mul_f32 v[222:223], v[14:15], v[238:239] op_sel_hi:[1,0]
	v_mov_b64_e32 v[14:15], 0
	v_pk_mul_f32 v[224:225], v[16:17], v[238:239] op_sel_hi:[1,0]
	v_mov_b64_e32 v[16:17], 0
	v_pk_mul_f32 v[226:227], v[10:11], v[238:239] op_sel_hi:[1,0]
	v_mov_b64_e32 v[10:11], 0
	v_pk_mul_f32 v[228:229], v[12:13], v[238:239] op_sel_hi:[1,0]
	v_mov_b64_e32 v[12:13], 0
	s_cmp_lg_u32 s79, 3
	s_cbranch_scc1 .Lp3f_ns13
	v_mul_f32_e32 v230, 0xbfb8aa3b, v222
	v_mul_f32_e32 v231, 0xbfb8aa3b, v223
	v_mul_f32_e32 v232, 0xbfb8aa3b, v224
	v_mul_f32_e32 v233, 0xbfb8aa3b, v225
	v_mul_f32_e32 v234, 0xbfb8aa3b, v226
	v_mul_f32_e32 v235, 0xbfb8aa3b, v227
	v_mul_f32_e32 v236, 0xbfb8aa3b, v228
	v_mul_f32_e32 v237, 0xbfb8aa3b, v229
	v_exp_f32_e32 v230, v230
	v_exp_f32_e32 v231, v231
	v_exp_f32_e32 v232, v232
	v_exp_f32_e32 v233, v233
	v_exp_f32_e32 v234, v234
	v_exp_f32_e32 v235, v235
	v_exp_f32_e32 v236, v236
	v_exp_f32_e32 v237, v237
	v_add_f32_e32 v230, 1.0, v230
	v_add_f32_e32 v231, 1.0, v231
	v_add_f32_e32 v232, 1.0, v232
	v_add_f32_e32 v233, 1.0, v233
	v_add_f32_e32 v234, 1.0, v234
	v_add_f32_e32 v235, 1.0, v235
	v_add_f32_e32 v236, 1.0, v236
	v_add_f32_e32 v237, 1.0, v237
	v_rcp_f32_e32 v230, v230
	v_rcp_f32_e32 v231, v231
	v_rcp_f32_e32 v232, v232
	v_rcp_f32_e32 v233, v233
	v_rcp_f32_e32 v234, v234
	v_rcp_f32_e32 v235, v235
	v_rcp_f32_e32 v236, v236
	v_rcp_f32_e32 v237, v237
	v_pk_mul_f32 v[222:223], v[222:223], v[230:231]
	v_pk_mul_f32 v[224:225], v[224:225], v[232:233]
	v_pk_mul_f32 v[226:227], v[226:227], v[234:235]
	v_pk_mul_f32 v[228:229], v[228:229], v[236:237]
; __device__ __forceinline__ unsigned pk2(float lo, float hi) { f32x2_t v = {lo, hi}; bf16x2_t b = __builtin_convertvector(v, bf16x2_t); return __builtin_bit_cast(unsigned, b); }
; __device__ __forceinline__ float siluf_(float x) { return x * sigmoidf_(x); }
; #define PG8_BAR __builtin_amdgcn_s_barrier()
;     __device__ __forceinline__ void operator()(Acc& acc, const Unit& u, int wr, int wc, int fr, int fq, const float (&rsa)[2][4]) const {
;     ...
;                 const int row = u.pm * BM + ai * HALF + wr * 64 + m * 16 + fr; const float rs = rsa[ai][m] * scale;
; #pragma unroll
;                 for (int bj = 0; bj < 2; ++bj) {
;                     const int within = bj * HALF + wc * 32 + 8 * fq;
;                     f32x4 v0 = acc[ai][bj][m][0] * rs, v1 = acc[ai][bj][m][1] * rs;
;                     if (mode == 3) { if (within < GRANK) { *(f32x4*)(GLR + (size_t)row * 16 + within) = v0; *(f32x4*)(GLR + (size_t)row * 16 + within + 4) = v1; } continue; }
;                     if (mode == 1) {
; #pragma unroll
;                         for (int j = 0; j < 4; ++j) { v0[j] = siluf_(v0[j]); v1[j] = siluf_(v1[j]); }
;                     }
;                     u32x4 w; w.x = pk2(v0[0], v0[1]); w.y = pk2(v0[2], v0[3]); w.z = pk2(v1[0], v1[1]); w.w = pk2(v1[2], v1[3]);
;                     *(u32x4*)(dst + (size_t)row * ld + cbase + within) = w;
; template <class Epi, bool ALIGN_EPI, bool ABLK = false>
; __device__ __forceinline__ void gemm_phase(PG8_LAS unsigned char* lds, const Gemm g, const StaticOrder& S, const Epi& E) {
;     ...
;         if (!has_next) break;
;         if (!E.keep(cur)) {
; #pragma unroll
;             for (int a = 0; a < 2; ++a)
; #pragma unroll
;                 for (int b = 0; b < 2; ++b)
; #pragma unroll
;                     for (int m = 0; m < 4; ++m)
; #pragma unroll
;                         for (int n = 0; n < 2; ++n) acc[a][b][m][n] = (f32x4){0.f, 0.f, 0.f, 0.f};
;         }
;         cur = nxt; cA = nA; cB = nB; ++ui;
;         if constexpr (ALIGN_EPI) { if (wr == 1) PG8_BAR; }
.Lp3f_ns13:
	v_cvt_pk_bf16_f32 v240, v222, v223
	v_cvt_pk_bf16_f32 v241, v224, v225
	v_cvt_pk_bf16_f32 v242, v226, v227
	v_cvt_pk_bf16_f32 v243, v228, v229
	ds_bpermute_b32 v248, v221, v240
	ds_bpermute_b32 v249, v221, v241
	ds_bpermute_b32 v250, v221, v242
	ds_bpermute_b32 v251, v221, v243
	s_waitcnt lgkmcnt(4)
	s_add_u32 s100, s98, 0x50000
	s_addc_u32 s101, s99, 0
	global_store_dwordx4 v220, v[244:247], s[100:101] offset:0
	v_mul_f32_e32 v238, s88, v133
	v_pk_mul_f32 v[222:223], v[38:39], v[238:239] op_sel_hi:[1,0]
	v_mov_b64_e32 v[38:39], 0
	v_pk_mul_f32 v[224:225], v[40:41], v[238:239] op_sel_hi:[1,0]
	v_mov_b64_e32 v[40:41], 0
	v_pk_mul_f32 v[226:227], v[34:35], v[238:239] op_sel_hi:[1,0]
	v_mov_b64_e32 v[34:35], 0
	v_pk_mul_f32 v[228:229], v[36:37], v[238:239] op_sel_hi:[1,0]
	v_mov_b64_e32 v[36:37], 0
	s_cmp_lg_u32 s79, 3
	s_cbranch_scc1 .Lp3f_ns14
	v_mul_f32_e32 v230, 0xbfb8aa3b, v222
	v_mul_f32_e32 v231, 0xbfb8aa3b, v223
	v_mul_f32_e32 v232, 0xbfb8aa3b, v224
	v_mul_f32_e32 v233, 0xbfb8aa3b, v225
	v_mul_f32_e32 v234, 0xbfb8aa3b, v226
	v_mul_f32_e32 v235, 0xbfb8aa3b, v227
	v_mul_f32_e32 v236, 0xbfb8aa3b, v228
	v_mul_f32_e32 v237, 0xbfb8aa3b, v229
	v_exp_f32_e32 v230, v230
	v_exp_f32_e32 v231, v231
	v_exp_f32_e32 v232, v232
	v_exp_f32_e32 v233, v233
	v_exp_f32_e32 v234, v234
	v_exp_f32_e32 v235, v235
	v_exp_f32_e32 v236, v236
	v_exp_f32_e32 v237, v237
	v_add_f32_e32 v230, 1.0, v230
	v_add_f32_e32 v231, 1.0, v231
	v_add_f32_e32 v232, 1.0, v232
	v_add_f32_e32 v233, 1.0, v233
	v_add_f32_e32 v234, 1.0, v234
	v_add_f32_e32 v235, 1.0, v235
	v_add_f32_e32 v236, 1.0, v236
	v_add_f32_e32 v237, 1.0, v237
	v_rcp_f32_e32 v230, v230
	v_rcp_f32_e32 v231, v231
	v_rcp_f32_e32 v232, v232
	v_rcp_f32_e32 v233, v233
	v_rcp_f32_e32 v234, v234
	v_rcp_f32_e32 v235, v235
	v_rcp_f32_e32 v236, v236
	v_rcp_f32_e32 v237, v237
	v_pk_mul_f32 v[222:223], v[222:223], v[230:231]
	v_pk_mul_f32 v[224:225], v[224:225], v[232:233]
	v_pk_mul_f32 v[226:227], v[226:227], v[234:235]
	v_pk_mul_f32 v[228:229], v[228:229], v[236:237]
.Lp3f_ns14:
	v_cvt_pk_bf16_f32 v240, v222, v223
	v_cvt_pk_bf16_f32 v241, v224, v225
	v_cvt_pk_bf16_f32 v242, v226, v227
	v_cvt_pk_bf16_f32 v243, v228, v229
	ds_bpermute_b32 v244, v221, v240
	ds_bpermute_b32 v245, v221, v241
	ds_bpermute_b32 v246, v221, v242
	ds_bpermute_b32 v247, v221, v243
	s_waitcnt lgkmcnt(4)
	s_add_u32 s100, s98, 0x50000
	s_addc_u32 s101, s99, 0
	global_store_dwordx4 v220, v[248:251], s[100:101] offset:256
	v_pk_mul_f32 v[222:223], v[6:7], v[238:239] op_sel_hi:[1,0]
	v_mov_b64_e32 v[6:7], 0
	v_pk_mul_f32 v[224:225], v[8:9], v[238:239] op_sel_hi:[1,0]
	v_mov_b64_e32 v[8:9], 0
	v_pk_mul_f32 v[226:227], v[2:3], v[238:239] op_sel_hi:[1,0]
	v_mov_b64_e32 v[2:3], 0
	v_pk_mul_f32 v[228:229], v[4:5], v[238:239] op_sel_hi:[1,0]
	v_mov_b64_e32 v[4:5], 0
	s_cmp_lg_u32 s79, 3
	s_cbranch_scc1 .Lp3f_ns15
	v_mul_f32_e32 v230, 0xbfb8aa3b, v222
	v_mul_f32_e32 v231, 0xbfb8aa3b, v223
	v_mul_f32_e32 v232, 0xbfb8aa3b, v224
	v_mul_f32_e32 v233, 0xbfb8aa3b, v225
	v_mul_f32_e32 v234, 0xbfb8aa3b, v226
	v_mul_f32_e32 v235, 0xbfb8aa3b, v227
	v_mul_f32_e32 v236, 0xbfb8aa3b, v228
	v_mul_f32_e32 v237, 0xbfb8aa3b, v229
	v_exp_f32_e32 v230, v230
	v_exp_f32_e32 v231, v231
	v_exp_f32_e32 v232, v232
	v_exp_f32_e32 v233, v233
	v_exp_f32_e32 v234, v234
	v_exp_f32_e32 v235, v235
	v_exp_f32_e32 v236, v236
	v_exp_f32_e32 v237, v237
	v_add_f32_e32 v230, 1.0, v230
	v_add_f32_e32 v231, 1.0, v231
	v_add_f32_e32 v232, 1.0, v232
	v_add_f32_e32 v233, 1.0, v233
	v_add_f32_e32 v234, 1.0, v234
	v_add_f32_e32 v235, 1.0, v235
	v_add_f32_e32 v236, 1.0, v236
	v_add_f32_e32 v237, 1.0, v237
	v_rcp_f32_e32 v230, v230
	v_rcp_f32_e32 v231, v231
	v_rcp_f32_e32 v232, v232
	v_rcp_f32_e32 v233, v233
	v_rcp_f32_e32 v234, v234
	v_rcp_f32_e32 v235, v235
	v_rcp_f32_e32 v236, v236
	v_rcp_f32_e32 v237, v237
	v_pk_mul_f32 v[222:223], v[222:223], v[230:231]
	v_pk_mul_f32 v[224:225], v[224:225], v[232:233]
	v_pk_mul_f32 v[226:227], v[226:227], v[234:235]
	v_pk_mul_f32 v[228:229], v[228:229], v[236:237]
.Lp3f_ns15:
	v_cvt_pk_bf16_f32 v240, v222, v223
	v_cvt_pk_bf16_f32 v241, v224, v225
	v_cvt_pk_bf16_f32 v242, v226, v227
	v_cvt_pk_bf16_f32 v243, v228, v229
	ds_bpermute_b32 v248, v221, v240
	ds_bpermute_b32 v249, v221, v241
	ds_bpermute_b32 v250, v221, v242
	ds_bpermute_b32 v251, v221, v243
	s_waitcnt lgkmcnt(4)
	s_add_u32 s100, s98, 0x58000
	s_addc_u32 s101, s99, 0
	global_store_dwordx4 v220, v[244:247], s[100:101] offset:0
	s_waitcnt lgkmcnt(0)
	s_add_u32 s100, s98, 0x58000
	s_addc_u32 s101, s99, 0
	global_store_dwordx4 v220, v[248:251], s[100:101] offset:256
	s_andn2_b64 vcc, exec, s[8:9]
	s_cbranch_vccnz .LBB0_814
	s_andn2_b64 vcc, exec, s[40:41]
	s_cbranch_vccnz .Lp3_nz
	s_barrier
.Lp3_nz:
	s_mov_b32 s30, s56
	s_mov_b32 s34, s54
	s_mov_b64 s[36:37], s[60:61]
	s_mov_b64 s[38:39], s[58:59]
	s_mov_b32 s44, s45
	s_branch .LBB0_814

; __device__ __forceinline__ unsigned pk2(float lo, float hi) { f32x2_t v = {lo, hi}; bf16x2_t b = __builtin_convertvector(v, bf16x2_t); return __builtin_bit_cast(unsigned, b); }
; __device__ __forceinline__ float siluf_(float x) { return x * sigmoidf_(x); }
;     __device__ __forceinline__ void operator()(Acc& acc, const Unit& u, int wr, int wc, int fr, int fq, const float (&rsa)[2][4]) const {
;     ...
;                 const int row = row0 + ai * HALF + m * 16; const float rs = rsa[ai][m];
;                 float o[8];
; #pragma unroll
;                 for (int n = 0; n < 2; ++n)
; #pragma unroll
;                     for (int j = 0; j < 4; ++j) { const float g = acc[ai][0][m][n][j] * rs, up = acc[ai][1][m][n][j] * rs; o[n * 4 + j] = siluf_(g) * up; }
;                 u32x4 w; w.x = pk2(o[0], o[1]); w.y = pk2(o[2], o[3]); w.z = pk2(o[4], o[5]); w.w = pk2(o[6], o[7]);
;                 const int rr = row & (BM - 1);
;                 *(u32x4*)((char*)O + ((size_t)(u.pm * (FF / BK) + (col0 >> 6))) * (2 * HTB) + (rr >> 7) * HTB + lds_byte(rr & 127, col0 & 63)) = w;
; template <class Epi, bool ALIGN_EPI, bool ABLK = false>
; __device__ __forceinline__ void gemm_phase(PG8_LAS unsigned char* lds, const Gemm g, const StaticOrder& S, const Epi& E) {
;     ...
;         if (!E.keep(cur)) {
; #pragma unroll
;             for (int a = 0; a < 2; ++a)
; #pragma unroll
;                 for (int b = 0; b < 2; ++b)
; #pragma unroll
;                     for (int m = 0; m < 4; ++m)
; #pragma unroll
;                         for (int n = 0; n < 2; ++n) acc[a][b][m][n] = (f32x4){0.f, 0.f, 0.f, 0.f};
;         }
.LBB0_2502:
	v_pk_mul_f32 v[178:179], v[126:127], v[134:135] op_sel_hi:[1,0]
	v_mov_b64_e32 v[126:127], 0
	v_pk_mul_f32 v[184:185], v[128:129], v[134:135] op_sel_hi:[1,0]
	v_mov_b64_e32 v[128:129], 0
	v_mul_f32_e32 v131, 0xbfb8aa3b, v178
	v_exp_f32_e32 v131, v131
	v_mul_f32_e32 v133, 0xbfb8aa3b, v179
	v_exp_f32_e32 v133, v133
	v_pk_mul_f32 v[182:183], v[94:95], v[134:135] op_sel_hi:[1,0]
	v_mov_b64_e32 v[94:95], 0
	v_add_f32_e32 v131, 1.0, v131
	v_rcp_f32_e32 v180, v131
	v_add_f32_e32 v131, 1.0, v133
	v_mul_f32_e32 v133, 0xbfb8aa3b, v184
	v_exp_f32_e32 v133, v133
	v_mul_f32_e32 v135, 0xbfb8aa3b, v185
	v_exp_f32_e32 v135, v135
	v_rcp_f32_e32 v181, v131
	v_add_f32_e32 v131, 1.0, v133
	v_rcp_f32_e32 v186, v131
	v_add_f32_e32 v131, 1.0, v135
	v_rcp_f32_e32 v187, v131
	v_pk_mul_f32 v[178:179], v[178:179], v[180:181]
	v_pk_mul_f32 v[180:181], v[96:97], v[134:135] op_sel_hi:[1,0]
	v_mov_b64_e32 v[96:97], 0
	v_pk_mul_f32 v[178:179], v[182:183], v[178:179]
	v_pk_mul_f32 v[182:183], v[184:185], v[186:187]
	v_pk_mul_f32 v[184:185], v[122:123], v[134:135] op_sel_hi:[1,0]
	v_mov_b64_e32 v[122:123], 0
	v_pk_mul_f32 v[188:189], v[124:125], v[134:135] op_sel_hi:[1,0]
	v_mov_b64_e32 v[124:125], 0
	v_mul_f32_e32 v131, 0xbfb8aa3b, v184
	v_exp_f32_e32 v131, v131
	v_mul_f32_e32 v133, 0xbfb8aa3b, v185
	v_exp_f32_e32 v133, v133
	v_pk_mul_f32 v[180:181], v[180:181], v[182:183]
	v_add_f32_e32 v131, 1.0, v131
	v_rcp_f32_e32 v182, v131
	v_add_f32_e32 v131, 1.0, v133
	v_mul_f32_e32 v133, 0xbfb8aa3b, v188
	v_pk_mul_f32 v[186:187], v[90:91], v[134:135] op_sel_hi:[1,0]
	v_mov_b64_e32 v[90:91], 0
	v_exp_f32_e32 v133, v133
	v_mul_f32_e32 v135, 0xbfb8aa3b, v189
	v_exp_f32_e32 v135, v135
	v_rcp_f32_e32 v183, v131
	s_lshl_b32 s51, s10, 7
	s_or_b32 s51, s51, s17
	s_ashr_i32 s51, s51, 6
	v_add_f32_e32 v131, 1.0, v133
	s_mul_i32 s53, s8, 44
	v_rcp_f32_e32 v190, v131
	v_add_f32_e32 v131, 1.0, v135
	v_pk_mul_f32 v[182:183], v[184:185], v[182:183]
	s_add_i32 s58, s51, s53
	v_rcp_f32_e32 v191, v131
	v_pk_mul_f32 v[182:183], v[186:187], v[182:183]
	s_ashr_i32 s59, s58, 31
	v_cvt_pk_bf16_f32 v178, v178, v179
	v_cvt_pk_bf16_f32 v179, v180, v181
	v_cvt_pk_bf16_f32 v180, v182, v183
	s_lshl_b64 s[58:59], s[58:59], 15
	v_pk_mul_f32 v[182:183], v[118:119], v[164:165] op_sel_hi:[1,0]
	v_mov_b64_e32 v[118:119], 0
	s_add_u32 s51, s14, s58
	v_mul_f32_e32 v131, 0xbfb8aa3b, v182
	s_addc_u32 s53, s15, s59
	v_exp_f32_e32 v131, v131
	v_mul_f32_e32 v133, 0xbfb8aa3b, v183
	v_pk_mul_f32 v[134:135], v[92:93], v[134:135] op_sel_hi:[1,0]
	v_mov_b64_e32 v[92:93], 0
	v_pk_mul_f32 v[184:185], v[188:189], v[190:191]
	s_add_u32 s58, s51, s73
	v_exp_f32_e32 v133, v133
	v_pk_mul_f32 v[134:135], v[134:135], v[184:185]
	s_addc_u32 s59, s53, 0
	v_cvt_pk_bf16_f32 v181, v134, v135
	v_lshl_add_u64 v[134:135], s[58:59], 0, v[144:145]
	global_store_dwordx4 v[134:135], v[178:181], off
	v_add_f32_e32 v131, 1.0, v131
	v_rcp_f32_e32 v134, v131
	v_pk_mul_f32 v[180:181], v[120:121], v[164:165] op_sel_hi:[1,0]
	v_mov_b64_e32 v[120:121], 0
	v_add_f32_e32 v131, 1.0, v133
	v_mul_f32_e32 v133, 0xbfb8aa3b, v180
	v_exp_f32_e32 v133, v133
	v_mul_f32_e32 v135, 0xbfb8aa3b, v181
	v_exp_f32_e32 v137, v135
	v_rcp_f32_e32 v135, v131
	v_add_f32_e32 v131, 1.0, v133
	v_rcp_f32_e32 v184, v131
	v_add_f32_e32 v131, 1.0, v137
	v_pk_mul_f32 v[134:135], v[182:183], v[134:135]
	v_pk_mul_f32 v[182:183], v[114:115], v[164:165] op_sel_hi:[1,0]
	v_mov_b64_e32 v[114:115], 0
	v_rcp_f32_e32 v185, v131
	v_mul_f32_e32 v131, 0xbfb8aa3b, v182
	v_exp_f32_e32 v131, v131
	v_mul_f32_e32 v133, 0xbfb8aa3b, v183
	v_exp_f32_e32 v133, v133
	v_pk_mul_f32 v[178:179], v[86:87], v[164:165] op_sel_hi:[1,0]
	v_mov_b64_e32 v[86:87], 0
	v_pk_mul_f32 v[180:181], v[180:181], v[184:185]
	v_pk_mul_f32 v[134:135], v[178:179], v[134:135]
	v_pk_mul_f32 v[178:179], v[88:89], v[164:165] op_sel_hi:[1,0]
	v_mov_b64_e32 v[88:89], 0
	v_add_f32_e32 v131, 1.0, v131
	v_pk_mul_f32 v[186:187], v[116:117], v[164:165] op_sel_hi:[1,0]
	v_mov_b64_e32 v[116:117], 0
	v_pk_mul_f32 v[180:181], v[178:179], v[180:181]
	v_rcp_f32_e32 v178, v131
	v_add_f32_e32 v131, 1.0, v133
	v_mul_f32_e32 v133, 0xbfb8aa3b, v186
	v_exp_f32_e32 v133, v133
	v_mul_f32_e32 v137, 0xbfb8aa3b, v187
	v_exp_f32_e32 v137, v137
	v_rcp_f32_e32 v179, v131
	v_add_f32_e32 v131, 1.0, v133
	v_rcp_f32_e32 v188, v131
	v_add_f32_e32 v131, 1.0, v137
	v_rcp_f32_e32 v189, v131
	v_pk_mul_f32 v[184:185], v[82:83], v[164:165] op_sel_hi:[1,0]
	v_mov_b64_e32 v[82:83], 0
	v_pk_mul_f32 v[178:179], v[182:183], v[178:179]
	s_nop 0
	v_pk_mul_f32 v[182:183], v[184:185], v[178:179]
	v_pk_mul_f32 v[178:179], v[84:85], v[164:165] op_sel_hi:[1,0]
	v_mov_b64_e32 v[84:85], 0
	v_pk_mul_f32 v[184:185], v[186:187], v[188:189]
	s_nop 0
	v_pk_mul_f32 v[184:185], v[178:179], v[184:185]
	v_cvt_pk_bf16_f32 v179, v180, v181
	v_cvt_pk_bf16_f32 v180, v182, v183
	v_pk_mul_f32 v[182:183], v[110:111], v[136:137] op_sel_hi:[1,0]
	v_mov_b64_e32 v[110:111], 0
	v_cvt_pk_bf16_f32 v178, v134, v135
	v_mul_f32_e32 v131, 0xbfb8aa3b, v182
	v_exp_f32_e32 v131, v131
	v_mul_f32_e32 v133, 0xbfb8aa3b, v183
	v_exp_f32_e32 v133, v133
	v_cvt_pk_bf16_f32 v181, v184, v185
	v_lshl_add_u64 v[134:135], s[58:59], 0, v[148:149]
	global_store_dwordx4 v[134:135], v[178:181], off
	v_add_f32_e32 v131, 1.0, v131
	v_rcp_f32_e32 v134, v131
	v_pk_mul_f32 v[180:181], v[112:113], v[136:137] op_sel_hi:[1,0]
	v_mov_b64_e32 v[112:113], 0
	v_add_f32_e32 v131, 1.0, v133
	v_mul_f32_e32 v133, 0xbfb8aa3b, v180
	v_exp_f32_e32 v133, v133
	v_mul_f32_e32 v135, 0xbfb8aa3b, v181
	v_pk_mul_f32 v[178:179], v[78:79], v[136:137] op_sel_hi:[1,0]
	v_mov_b64_e32 v[78:79], 0
	v_exp_f32_e32 v137, v135
	v_rcp_f32_e32 v135, v131
; __device__ __forceinline__ unsigned pk2(float lo, float hi) { f32x2_t v = {lo, hi}; bf16x2_t b = __builtin_convertvector(v, bf16x2_t); return __builtin_bit_cast(unsigned, b); }
; __device__ __forceinline__ float siluf_(float x) { return x * sigmoidf_(x); }
;     __device__ __forceinline__ void operator()(Acc& acc, const Unit& u, int wr, int wc, int fr, int fq, const float (&rsa)[2][4]) const {
;     ...
;                 const int row = row0 + ai * HALF + m * 16; const float rs = rsa[ai][m];
;                 float o[8];
; #pragma unroll
;                 for (int n = 0; n < 2; ++n)
; #pragma unroll
;                     for (int j = 0; j < 4; ++j) { const float g = acc[ai][0][m][n][j] * rs, up = acc[ai][1][m][n][j] * rs; o[n * 4 + j] = siluf_(g) * up; }
;                 u32x4 w; w.x = pk2(o[0], o[1]); w.y = pk2(o[2], o[3]); w.z = pk2(o[4], o[5]); w.w = pk2(o[6], o[7]);
;                 const int rr = row & (BM - 1);
;                 *(u32x4*)((char*)O + ((size_t)(u.pm * (FF / BK) + (col0 >> 6))) * (2 * HTB) + (rr >> 7) * HTB + lds_byte(rr & 127, col0 & 63)) = w;
; template <class Epi, bool ALIGN_EPI, bool ABLK = false>
; __device__ __forceinline__ void gemm_phase(PG8_LAS unsigned char* lds, const Gemm g, const StaticOrder& S, const Epi& E) {
;     ...
;         if (!E.keep(cur)) {
; #pragma unroll
;             for (int a = 0; a < 2; ++a)
; #pragma unroll
;                 for (int b = 0; b < 2; ++b)
; #pragma unroll
;                     for (int m = 0; m < 4; ++m)
; #pragma unroll
;                         for (int n = 0; n < 2; ++n) acc[a][b][m][n] = (f32x4){0.f, 0.f, 0.f, 0.f};
;         }
	v_add_f32_e32 v131, 1.0, v133
	v_rcp_f32_e32 v184, v131
	v_add_f32_e32 v131, 1.0, v137
	v_pk_mul_f32 v[134:135], v[182:183], v[134:135]
	v_pk_mul_f32 v[182:183], v[106:107], v[136:137] op_sel_hi:[1,0]
	v_mov_b64_e32 v[106:107], 0
	v_rcp_f32_e32 v185, v131
	v_mul_f32_e32 v131, 0xbfb8aa3b, v182
	v_exp_f32_e32 v131, v131
	v_mul_f32_e32 v133, 0xbfb8aa3b, v183
	v_exp_f32_e32 v133, v133
	v_pk_mul_f32 v[134:135], v[178:179], v[134:135]
	v_pk_mul_f32 v[178:179], v[80:81], v[136:137] op_sel_hi:[1,0]
	v_mov_b64_e32 v[80:81], 0
	v_pk_mul_f32 v[180:181], v[180:181], v[184:185]
	v_add_f32_e32 v131, 1.0, v131
	v_pk_mul_f32 v[186:187], v[108:109], v[136:137] op_sel_hi:[1,0]
	v_mov_b64_e32 v[108:109], 0
	v_pk_mul_f32 v[178:179], v[178:179], v[180:181]
	v_rcp_f32_e32 v180, v131
	v_add_f32_e32 v131, 1.0, v133
	v_mul_f32_e32 v133, 0xbfb8aa3b, v186
	v_pk_mul_f32 v[184:185], v[74:75], v[136:137] op_sel_hi:[1,0]
	v_mov_b64_e32 v[74:75], 0
	v_exp_f32_e32 v133, v133
	v_mul_f32_e32 v137, 0xbfb8aa3b, v187
	v_exp_f32_e32 v137, v137
	v_rcp_f32_e32 v181, v131
	v_add_f32_e32 v131, 1.0, v133
	v_rcp_f32_e32 v188, v131
	v_add_f32_e32 v131, 1.0, v137
	v_rcp_f32_e32 v189, v131
	v_pk_mul_f32 v[180:181], v[182:183], v[180:181]
	v_pk_mul_f32 v[136:137], v[76:77], v[136:137] op_sel_hi:[1,0]
	v_mov_b64_e32 v[76:77], 0
	v_pk_mul_f32 v[180:181], v[184:185], v[180:181]
	v_pk_mul_f32 v[182:183], v[186:187], v[188:189]
	v_cvt_pk_bf16_f32 v134, v134, v135
	v_pk_mul_f32 v[182:183], v[136:137], v[182:183]
	v_cvt_pk_bf16_f32 v136, v180, v181
	v_pk_mul_f32 v[180:181], v[102:103], v[162:163] op_sel_hi:[1,0]
	v_mov_b64_e32 v[102:103], 0
	v_cvt_pk_bf16_f32 v135, v178, v179
	v_mul_f32_e32 v131, 0xbfb8aa3b, v180
	v_exp_f32_e32 v131, v131
	v_mul_f32_e32 v133, 0xbfb8aa3b, v181
	v_exp_f32_e32 v133, v133
	v_cvt_pk_bf16_f32 v137, v182, v183
	v_lshl_add_u64 v[178:179], s[58:59], 0, v[150:151]
	global_store_dwordx4 v[178:179], v[134:137], off
	v_add_f32_e32 v131, 1.0, v131
	v_pk_mul_f32 v[178:179], v[104:105], v[162:163] op_sel_hi:[1,0]
	v_mov_b64_e32 v[104:105], 0
	v_rcp_f32_e32 v134, v131
	v_add_f32_e32 v131, 1.0, v133
	v_mul_f32_e32 v133, 0xbfb8aa3b, v178
	v_exp_f32_e32 v133, v133
	v_mul_f32_e32 v135, 0xbfb8aa3b, v179
	v_exp_f32_e32 v164, v135
	v_rcp_f32_e32 v135, v131
	v_add_f32_e32 v131, 1.0, v133
	v_rcp_f32_e32 v182, v131
	v_add_f32_e32 v131, 1.0, v164
	v_pk_mul_f32 v[134:135], v[180:181], v[134:135]
	v_pk_mul_f32 v[180:181], v[98:99], v[162:163] op_sel_hi:[1,0]
	v_mov_b64_e32 v[98:99], 0
	v_rcp_f32_e32 v183, v131
	v_mul_f32_e32 v131, 0xbfb8aa3b, v180
	v_exp_f32_e32 v131, v131
	v_mul_f32_e32 v133, 0xbfb8aa3b, v181
	v_exp_f32_e32 v133, v133
	v_pk_mul_f32 v[136:137], v[70:71], v[162:163] op_sel_hi:[1,0]
	v_mov_b64_e32 v[70:71], 0
	v_pk_mul_f32 v[178:179], v[178:179], v[182:183]
	v_pk_mul_f32 v[134:135], v[136:137], v[134:135]
	v_pk_mul_f32 v[136:137], v[72:73], v[162:163] op_sel_hi:[1,0]
	v_mov_b64_e32 v[72:73], 0
	v_add_f32_e32 v131, 1.0, v131
	v_pk_mul_f32 v[184:185], v[100:101], v[162:163] op_sel_hi:[1,0]
	v_mov_b64_e32 v[100:101], 0
	v_pk_mul_f32 v[136:137], v[136:137], v[178:179]
	v_rcp_f32_e32 v178, v131
	v_add_f32_e32 v131, 1.0, v133
	v_mul_f32_e32 v133, 0xbfb8aa3b, v184
	v_exp_f32_e32 v133, v133
	v_mul_f32_e32 v164, 0xbfb8aa3b, v185
	v_exp_f32_e32 v164, v164
	v_rcp_f32_e32 v179, v131
	v_add_f32_e32 v131, 1.0, v133
	v_rcp_f32_e32 v186, v131
	v_add_f32_e32 v131, 1.0, v164
	v_rcp_f32_e32 v187, v131
	v_pk_mul_f32 v[182:183], v[66:67], v[162:163] op_sel_hi:[1,0]
	v_mov_b64_e32 v[66:67], 0
	v_pk_mul_f32 v[178:179], v[180:181], v[178:179]
	v_pk_mul_f32 v[180:181], v[68:69], v[162:163] op_sel_hi:[1,0]
	v_mov_b64_e32 v[68:69], 0
	v_pk_mul_f32 v[178:179], v[182:183], v[178:179]
	v_pk_mul_f32 v[182:183], v[184:185], v[186:187]
	v_cvt_pk_bf16_f32 v134, v134, v135
	v_pk_mul_f32 v[180:181], v[180:181], v[182:183]
	v_cvt_pk_bf16_f32 v135, v136, v137
	v_cvt_pk_bf16_f32 v137, v180, v181
	v_pk_mul_f32 v[180:181], v[62:63], v[130:131] op_sel_hi:[1,0]
	v_mov_b64_e32 v[62:63], 0
	v_cvt_pk_bf16_f32 v136, v178, v179
	v_mul_f32_e32 v131, 0xbfb8aa3b, v180
	v_exp_f32_e32 v131, v131
	v_mul_f32_e32 v133, 0xbfb8aa3b, v181
	v_exp_f32_e32 v133, v133
	v_lshl_add_u64 v[178:179], s[58:59], 0, v[152:153]
	v_add_f32_e32 v131, 1.0, v131
	global_store_dwordx4 v[178:179], v[134:137], off
	s_add_u32 s58, s51, s74
	s_addc_u32 s59, s53, 0
	v_rcp_f32_e32 v134, v131
	v_pk_mul_f32 v[136:137], v[30:31], v[130:131] op_sel_hi:[1,0]
	v_mov_b64_e32 v[30:31], 0
	v_add_f32_e32 v131, 1.0, v133
	v_pk_mul_f32 v[178:179], v[64:65], v[130:131] op_sel_hi:[1,0]
	v_mov_b64_e32 v[64:65], 0
	s_andn2_b64 vcc, exec, s[6:7]
	v_mul_f32_e32 v133, 0xbfb8aa3b, v178
	v_exp_f32_e32 v133, v133
	v_mul_f32_e32 v135, 0xbfb8aa3b, v179
	v_exp_f32_e32 v162, v135
	v_rcp_f32_e32 v135, v131
	v_add_f32_e32 v131, 1.0, v133
	v_rcp_f32_e32 v182, v131
	v_add_f32_e32 v131, 1.0, v162
	v_pk_mul_f32 v[134:135], v[180:181], v[134:135]
	v_pk_mul_f32 v[180:181], v[58:59], v[130:131] op_sel_hi:[1,0]
	v_mov_b64_e32 v[58:59], 0
	v_rcp_f32_e32 v183, v131
	v_pk_mul_f32 v[134:135], v[136:137], v[134:135]
	v_pk_mul_f32 v[136:137], v[32:33], v[130:131] op_sel_hi:[1,0]
	v_mov_b64_e32 v[32:33], 0
	v_mul_f32_e32 v131, 0xbfb8aa3b, v180
	v_exp_f32_e32 v131, v131
	v_mul_f32_e32 v133, 0xbfb8aa3b, v181
	v_exp_f32_e32 v133, v133
	v_pk_mul_f32 v[178:179], v[178:179], v[182:183]
	v_add_f32_e32 v131, 1.0, v131
	v_pk_mul_f32 v[136:137], v[136:137], v[178:179]
	v_rcp_f32_e32 v178, v131
	v_pk_mul_f32 v[182:183], v[26:27], v[130:131] op_sel_hi:[1,0]
	v_mov_b64_e32 v[26:27], 0
	v_add_f32_e32 v131, 1.0, v133
	v_pk_mul_f32 v[184:185], v[60:61], v[130:131] op_sel_hi:[1,0]
	v_mov_b64_e32 v[60:61], 0
; __device__ __forceinline__ unsigned pk2(float lo, float hi) { f32x2_t v = {lo, hi}; bf16x2_t b = __builtin_convertvector(v, bf16x2_t); return __builtin_bit_cast(unsigned, b); }
; __device__ __forceinline__ float siluf_(float x) { return x * sigmoidf_(x); }
;     __device__ __forceinline__ void operator()(Acc& acc, const Unit& u, int wr, int wc, int fr, int fq, const float (&rsa)[2][4]) const {
;     ...
;                 const int row = row0 + ai * HALF + m * 16; const float rs = rsa[ai][m];
;                 float o[8];
; #pragma unroll
;                 for (int n = 0; n < 2; ++n)
; #pragma unroll
;                     for (int j = 0; j < 4; ++j) { const float g = acc[ai][0][m][n][j] * rs, up = acc[ai][1][m][n][j] * rs; o[n * 4 + j] = siluf_(g) * up; }
;                 u32x4 w; w.x = pk2(o[0], o[1]); w.y = pk2(o[2], o[3]); w.z = pk2(o[4], o[5]); w.w = pk2(o[6], o[7]);
;                 const int rr = row & (BM - 1);
;                 *(u32x4*)((char*)O + ((size_t)(u.pm * (FF / BK) + (col0 >> 6))) * (2 * HTB) + (rr >> 7) * HTB + lds_byte(rr & 127, col0 & 63)) = w;
; template <class Epi, bool ALIGN_EPI, bool ABLK = false>
; __device__ __forceinline__ void gemm_phase(PG8_LAS unsigned char* lds, const Gemm g, const StaticOrder& S, const Epi& E) {
;     ...
;         if (!E.keep(cur)) {
; #pragma unroll
;             for (int a = 0; a < 2; ++a)
; #pragma unroll
;                 for (int b = 0; b < 2; ++b)
; #pragma unroll
;                     for (int m = 0; m < 4; ++m)
; #pragma unroll
;                         for (int n = 0; n < 2; ++n) acc[a][b][m][n] = (f32x4){0.f, 0.f, 0.f, 0.f};
;         }
	v_rcp_f32_e32 v179, v131
	v_mul_f32_e32 v133, 0xbfb8aa3b, v184
	v_exp_f32_e32 v133, v133
	v_mul_f32_e32 v162, 0xbfb8aa3b, v185
	v_exp_f32_e32 v162, v162
	v_pk_mul_f32 v[178:179], v[180:181], v[178:179]
	v_add_f32_e32 v131, 1.0, v133
	v_rcp_f32_e32 v186, v131
	v_add_f32_e32 v131, 1.0, v162
	v_rcp_f32_e32 v187, v131
	v_pk_mul_f32 v[178:179], v[182:183], v[178:179]
	v_cvt_pk_bf16_f32 v134, v134, v135
	v_cvt_pk_bf16_f32 v135, v136, v137
	v_cvt_pk_bf16_f32 v136, v178, v179
	v_pk_mul_f32 v[178:179], v[54:55], v[160:161] op_sel_hi:[1,0]
	v_mov_b64_e32 v[54:55], 0
	v_pk_mul_f32 v[130:131], v[28:29], v[130:131] op_sel_hi:[1,0]
	v_mov_b64_e32 v[28:29], 0
	v_mul_f32_e32 v133, 0xbfb8aa3b, v178
	v_pk_mul_f32 v[180:181], v[184:185], v[186:187]
	v_exp_f32_e32 v133, v133
	v_pk_mul_f32 v[130:131], v[130:131], v[180:181]
	v_pk_mul_f32 v[182:183], v[52:53], v[160:161] op_sel_hi:[1,0]
	v_mov_b64_e32 v[52:53], 0
	v_cvt_pk_bf16_f32 v137, v130, v131
	v_lshl_add_u64 v[130:131], s[58:59], 0, v[144:145]
	global_store_dwordx4 v[130:131], v[134:137], off
	v_mul_f32_e32 v130, 0xbfb8aa3b, v179
	v_exp_f32_e32 v131, v130
	v_pk_mul_f32 v[136:137], v[56:57], v[160:161] op_sel_hi:[1,0]
	v_mov_b64_e32 v[56:57], 0
	v_add_f32_e32 v130, 1.0, v133
	v_mul_f32_e32 v133, 0xbfb8aa3b, v136
	v_exp_f32_e32 v133, v133
	v_mul_f32_e32 v162, 0xbfb8aa3b, v137
	v_exp_f32_e32 v162, v162
	v_add_f32_e32 v131, 1.0, v131
	v_add_f32_e32 v133, 1.0, v133
	v_rcp_f32_e32 v130, v130
	v_rcp_f32_e32 v131, v131
	v_rcp_f32_e32 v180, v133
	v_add_f32_e32 v133, 1.0, v162
	v_rcp_f32_e32 v181, v133
	v_pk_mul_f32 v[134:135], v[22:23], v[160:161] op_sel_hi:[1,0]
	v_mov_b64_e32 v[22:23], 0
	v_pk_mul_f32 v[130:131], v[178:179], v[130:131]
	v_pk_mul_f32 v[178:179], v[50:51], v[160:161] op_sel_hi:[1,0]
	v_mov_b64_e32 v[50:51], 0
	v_pk_mul_f32 v[130:131], v[134:135], v[130:131]
	v_pk_mul_f32 v[134:135], v[24:25], v[160:161] op_sel_hi:[1,0]
	v_mov_b64_e32 v[24:25], 0
	v_pk_mul_f32 v[136:137], v[136:137], v[180:181]
	v_mul_f32_e32 v133, 0xbfb8aa3b, v178
	v_exp_f32_e32 v133, v133
	v_pk_mul_f32 v[136:137], v[134:135], v[136:137]
	v_mul_f32_e32 v134, 0xbfb8aa3b, v179
	v_exp_f32_e32 v135, v134
	v_add_f32_e32 v133, 1.0, v133
	v_rcp_f32_e32 v134, v133
	v_pk_mul_f32 v[180:181], v[18:19], v[160:161] op_sel_hi:[1,0]
	v_mov_b64_e32 v[18:19], 0
	v_add_f32_e32 v133, 1.0, v135
	v_mul_f32_e32 v135, 0xbfb8aa3b, v182
	v_exp_f32_e32 v162, v135
	v_mul_f32_e32 v135, 0xbfb8aa3b, v183
	v_exp_f32_e32 v164, v135
	v_rcp_f32_e32 v135, v133
	v_add_f32_e32 v133, 1.0, v162
	v_rcp_f32_e32 v184, v133
	v_add_f32_e32 v133, 1.0, v164
	v_rcp_f32_e32 v185, v133
	v_pk_mul_f32 v[134:135], v[178:179], v[134:135]
	s_nop 0
	v_pk_mul_f32 v[178:179], v[180:181], v[134:135]
	v_pk_mul_f32 v[134:135], v[20:21], v[160:161] op_sel_hi:[1,0]
	v_mov_b64_e32 v[20:21], 0
	v_pk_mul_f32 v[180:181], v[182:183], v[184:185]
	s_nop 0
	v_pk_mul_f32 v[180:181], v[134:135], v[180:181]
	v_cvt_pk_bf16_f32 v135, v136, v137
	v_cvt_pk_bf16_f32 v136, v178, v179
	v_pk_mul_f32 v[178:179], v[46:47], v[132:133] op_sel_hi:[1,0]
	v_mov_b64_e32 v[46:47], 0
	v_cvt_pk_bf16_f32 v134, v130, v131
	v_mul_f32_e32 v133, 0xbfb8aa3b, v178
	v_exp_f32_e32 v133, v133
	v_cvt_pk_bf16_f32 v137, v180, v181
	v_lshl_add_u64 v[130:131], s[58:59], 0, v[148:149]
	global_store_dwordx4 v[130:131], v[134:137], off
	v_mul_f32_e32 v130, 0xbfb8aa3b, v179
	v_exp_f32_e32 v131, v130
	v_pk_mul_f32 v[136:137], v[48:49], v[132:133] op_sel_hi:[1,0]
	v_mov_b64_e32 v[48:49], 0
	v_add_f32_e32 v130, 1.0, v133
	v_pk_mul_f32 v[134:135], v[14:15], v[132:133] op_sel_hi:[1,0]
	v_mov_b64_e32 v[14:15], 0
	v_mul_f32_e32 v133, 0xbfb8aa3b, v136
	v_exp_f32_e32 v133, v133
	v_mul_f32_e32 v160, 0xbfb8aa3b, v137
	v_exp_f32_e32 v160, v160
	v_add_f32_e32 v131, 1.0, v131
	v_add_f32_e32 v133, 1.0, v133
	v_rcp_f32_e32 v130, v130
	v_rcp_f32_e32 v131, v131
	v_rcp_f32_e32 v180, v133
	v_add_f32_e32 v133, 1.0, v160
	v_rcp_f32_e32 v181, v133
	v_pk_mul_f32 v[130:131], v[178:179], v[130:131]
	v_pk_mul_f32 v[178:179], v[42:43], v[132:133] op_sel_hi:[1,0]
; __device__ __forceinline__ unsigned pk2(float lo, float hi) { f32x2_t v = {lo, hi}; bf16x2_t b = __builtin_convertvector(v, bf16x2_t); return __builtin_bit_cast(unsigned, b); }
; __device__ __forceinline__ float siluf_(float x) { return x * sigmoidf_(x); }
; #define PG8_BAR __builtin_amdgcn_s_barrier()
;     __device__ __forceinline__ void operator()(Acc& acc, const Unit& u, int wr, int wc, int fr, int fq, const float (&rsa)[2][4]) const {
;     ...
;                 const int row = row0 + ai * HALF + m * 16; const float rs = rsa[ai][m];
;                 float o[8];
; #pragma unroll
;                 for (int n = 0; n < 2; ++n)
; #pragma unroll
;                     for (int j = 0; j < 4; ++j) { const float g = acc[ai][0][m][n][j] * rs, up = acc[ai][1][m][n][j] * rs; o[n * 4 + j] = siluf_(g) * up; }
;                 u32x4 w; w.x = pk2(o[0], o[1]); w.y = pk2(o[2], o[3]); w.z = pk2(o[4], o[5]); w.w = pk2(o[6], o[7]);
;                 const int rr = row & (BM - 1);
;                 *(u32x4*)((char*)O + ((size_t)(u.pm * (FF / BK) + (col0 >> 6))) * (2 * HTB) + (rr >> 7) * HTB + lds_byte(rr & 127, col0 & 63)) = w;
; template <class Epi, bool ALIGN_EPI, bool ABLK = false>
; __device__ __forceinline__ void gemm_phase(PG8_LAS unsigned char* lds, const Gemm g, const StaticOrder& S, const Epi& E) {
;     ...
;         if (!has_next) break;
;         if (!E.keep(cur)) {
; #pragma unroll
;             for (int a = 0; a < 2; ++a)
; #pragma unroll
;                 for (int b = 0; b < 2; ++b)
; #pragma unroll
;                     for (int m = 0; m < 4; ++m)
; #pragma unroll
;                         for (int n = 0; n < 2; ++n) acc[a][b][m][n] = (f32x4){0.f, 0.f, 0.f, 0.f};
;         }
;         cur = nxt; cA = nA; cB = nB; ++ui;
;         if constexpr (ALIGN_EPI) { if (wr == 1) PG8_BAR; }
	v_mov_b64_e32 v[42:43], 0
	v_pk_mul_f32 v[130:131], v[134:135], v[130:131]
	v_pk_mul_f32 v[134:135], v[16:17], v[132:133] op_sel_hi:[1,0]
	v_mov_b64_e32 v[16:17], 0
	v_pk_mul_f32 v[136:137], v[136:137], v[180:181]
	v_mul_f32_e32 v133, 0xbfb8aa3b, v178
	v_exp_f32_e32 v133, v133
	v_pk_mul_f32 v[134:135], v[134:135], v[136:137]
	v_mul_f32_e32 v136, 0xbfb8aa3b, v179
	v_exp_f32_e32 v137, v136
	v_add_f32_e32 v133, 1.0, v133
	v_rcp_f32_e32 v136, v133
	v_pk_mul_f32 v[180:181], v[10:11], v[132:133] op_sel_hi:[1,0]
	v_mov_b64_e32 v[10:11], 0
	v_add_f32_e32 v133, 1.0, v137
	v_pk_mul_f32 v[182:183], v[44:45], v[132:133] op_sel_hi:[1,0]
	v_mov_b64_e32 v[44:45], 0
	v_cvt_pk_bf16_f32 v130, v130, v131
	v_mul_f32_e32 v137, 0xbfb8aa3b, v182
	v_exp_f32_e32 v160, v137
	v_mul_f32_e32 v137, 0xbfb8aa3b, v183
	v_exp_f32_e32 v162, v137
	v_rcp_f32_e32 v137, v133
	v_add_f32_e32 v133, 1.0, v160
	v_rcp_f32_e32 v184, v133
	v_add_f32_e32 v133, 1.0, v162
	v_rcp_f32_e32 v185, v133
	v_pk_mul_f32 v[136:137], v[178:179], v[136:137]
	v_pk_mul_f32 v[132:133], v[12:13], v[132:133] op_sel_hi:[1,0]
	v_mov_b64_e32 v[12:13], 0
	v_pk_mul_f32 v[136:137], v[180:181], v[136:137]
	v_pk_mul_f32 v[178:179], v[182:183], v[184:185]
	v_cvt_pk_bf16_f32 v131, v134, v135
	v_pk_mul_f32 v[178:179], v[132:133], v[178:179]
	v_cvt_pk_bf16_f32 v132, v136, v137
	v_pk_mul_f32 v[136:137], v[38:39], v[158:159] op_sel_hi:[1,0]
	v_mov_b64_e32 v[38:39], 0
	v_cvt_pk_bf16_f32 v133, v178, v179
	v_mul_f32_e32 v160, 0xbfb8aa3b, v136
	v_lshl_add_u64 v[134:135], s[58:59], 0, v[150:151]
	v_exp_f32_e32 v160, v160
	global_store_dwordx4 v[134:135], v[130:133], off
	v_pk_mul_f32 v[134:135], v[40:41], v[158:159] op_sel_hi:[1,0]
	v_mov_b64_e32 v[40:41], 0
	v_pk_mul_f32 v[180:181], v[36:37], v[158:159] op_sel_hi:[1,0]
	v_mov_b64_e32 v[36:37], 0
	v_mul_f32_e32 v130, 0xbfb8aa3b, v137
	v_exp_f32_e32 v131, v130
	v_add_f32_e32 v130, 1.0, v160
	v_mul_f32_e32 v160, 0xbfb8aa3b, v134
	v_exp_f32_e32 v160, v160
	v_mul_f32_e32 v162, 0xbfb8aa3b, v135
	v_add_f32_e32 v131, 1.0, v131
	v_exp_f32_e32 v162, v162
	v_rcp_f32_e32 v130, v130
	v_rcp_f32_e32 v131, v131
	v_add_f32_e32 v160, 1.0, v160
	v_rcp_f32_e32 v178, v160
	v_add_f32_e32 v160, 1.0, v162
	v_rcp_f32_e32 v179, v160
	v_pk_mul_f32 v[130:131], v[136:137], v[130:131]
	v_pk_mul_f32 v[136:137], v[34:35], v[158:159] op_sel_hi:[1,0]
	v_mov_b64_e32 v[34:35], 0
	v_pk_mul_f32 v[132:133], v[6:7], v[158:159] op_sel_hi:[1,0]
	v_mov_b64_e32 v[6:7], 0
	v_mul_f32_e32 v160, 0xbfb8aa3b, v136
	v_exp_f32_e32 v160, v160
	v_pk_mul_f32 v[130:131], v[132:133], v[130:131]
	v_pk_mul_f32 v[132:133], v[8:9], v[158:159] op_sel_hi:[1,0]
	v_mov_b64_e32 v[8:9], 0
	v_pk_mul_f32 v[134:135], v[134:135], v[178:179]
	v_mul_f32_e32 v162, 0xbfb8aa3b, v181
	v_pk_mul_f32 v[132:133], v[132:133], v[134:135]
	v_mul_f32_e32 v134, 0xbfb8aa3b, v137
	v_exp_f32_e32 v135, v134
	v_add_f32_e32 v134, 1.0, v160
	v_mul_f32_e32 v160, 0xbfb8aa3b, v180
	v_exp_f32_e32 v160, v160
	v_exp_f32_e32 v162, v162
	v_add_f32_e32 v135, 1.0, v135
	v_rcp_f32_e32 v134, v134
	v_add_f32_e32 v160, 1.0, v160
	v_rcp_f32_e32 v135, v135
	v_rcp_f32_e32 v182, v160
	v_add_f32_e32 v160, 1.0, v162
	v_rcp_f32_e32 v183, v160
	v_pk_mul_f32 v[178:179], v[2:3], v[158:159] op_sel_hi:[1,0]
	v_mov_b64_e32 v[2:3], 0
	v_pk_mul_f32 v[134:135], v[136:137], v[134:135]
	v_pk_mul_f32 v[136:137], v[4:5], v[158:159] op_sel_hi:[1,0]
	v_mov_b64_e32 v[4:5], 0
	v_pk_mul_f32 v[134:135], v[178:179], v[134:135]
	v_pk_mul_f32 v[178:179], v[180:181], v[182:183]
	v_cvt_pk_bf16_f32 v130, v130, v131
	v_pk_mul_f32 v[136:137], v[136:137], v[178:179]
	v_cvt_pk_bf16_f32 v131, v132, v133
	v_cvt_pk_bf16_f32 v132, v134, v135
	v_cvt_pk_bf16_f32 v133, v136, v137
	v_lshl_add_u64 v[134:135], s[58:59], 0, v[152:153]
	global_store_dwordx4 v[134:135], v[130:133], off
	s_cbranch_vccnz .LBB0_2491
	s_andn2_b64 vcc, exec, s[26:27]
	s_cbranch_vccnz .Lp9_nz
	s_barrier
.Lp9_nz:
	s_mov_b32 s8, s52
	s_mov_b32 s10, s50
	s_mov_b64 s[22:23], s[56:57]
	s_mov_b64 s[24:25], s[54:55]
	s_mov_b32 s71, s78
	s_branch .LBB0_2491
